# gdn forward substitution: LDS prefetch depth 7 (was 3)
# baseline (speedup 1.0000x reference)
.LBB0_416:
	s_or_b64 exec, exec, s[40:41]
	s_waitcnt lgkmcnt(0)
	s_barrier
	s_and_saveexec_b64 s[48:49], s[46:47]
	s_cbranch_execz .LBB0_256
	v_add_u32_e32 v0, 0x8200, v1
	v_add_u32_e32 v2, 0x4000, v1
	v_cndmask_b32_e64 v3, v233, v252, s[44:45]
	v_cndmask_b32_e64 v69, v2, v0, s[44:45]
	v_add_u32_e32 v0, v1, v3
	ds_read_b32 v8, v0
	ds_read_b128 v[12:15], v129 offset:50944
	v_mov_b32_e32 v0, 0x10400
	v_mov_b32_e32 v4, 0x10600
	ds_read_b128 v[0:3], v0
	ds_read_b128 v[4:7], v4
	s_waitcnt lgkmcnt(0)
	v_cndmask_b32_e64 v0, v4, v0, s[44:45]
	ds_read_b32 v4, v129 offset:50176
	v_fma_f32 v0, v8, v0, 0
	ds_read2_b32 v[8:9], v69 offset0:65 offset1:130
	v_cndmask_b32_e64 v1, v5, v1, s[44:45]
	v_cndmask_b32_e64 v2, v6, v2, s[44:45]
	s_waitcnt lgkmcnt(1)
	v_mul_f32_e32 v4, v0, v4
	v_cndmask_b32_e64 v3, v7, v3, s[44:45]
	s_waitcnt lgkmcnt(0)
	v_fma_f32 v1, v8, v1, -v4
	ds_read_b64 v[4:5], v129 offset:50432
	v_add_f32_e32 v1, 0, v1
	v_mov_b32_e32 v8, 0x10610
	s_waitcnt lgkmcnt(0)
	v_mul_f32_e32 v4, v0, v4
	v_fma_f32 v2, v9, v2, -v4
	v_fma_f32 v4, -v1, v5, 0
	v_add_f32_e32 v2, v2, v4
	v_add_u32_e32 v4, 0x200, v69
	ds_read2_b32 v[16:17], v4 offset0:67 offset1:132
	ds_read_b96 v[4:6], v129 offset:50688
	ds_read_b128 v[8:11], v8
	s_waitcnt lgkmcnt(1)
	v_mul_f32_e32 v4, v0, v4
	v_fma_f32 v3, v16, v3, -v4
	v_fma_f32 v4, -v1, v5, 0
	v_fma_f32 v5, -v2, v6, 0
	v_add_f32_e32 v3, v3, v4
	v_mov_b32_e32 v4, 0x10410
	v_add_f32_e32 v3, v3, v5
	ds_read_b128 v[4:7], v4
	s_waitcnt lgkmcnt(0)
	v_cndmask_b32_e64 v4, v8, v4, s[44:45]
	v_mul_f32_e32 v8, v0, v12
	v_fma_f32 v4, v17, v4, -v8
	v_fma_f32 v8, -v1, v13, 0
	v_fma_f32 v12, -v2, v14, 0
	v_fma_f32 v13, -v3, v15, 0
	v_add_f32_e32 v4, v4, v8
	v_add_f32_e32 v8, v12, v13
	v_add_f32_e32 v4, v4, v8
	v_add_u32_e32 v8, 0x400, v69
	ds_read_b128 v[12:15], v129 offset:51200
	ds_read2_b32 v[16:17], v8 offset0:69 offset1:134
	v_cndmask_b32_e64 v5, v9, v5, s[44:45]
	v_cndmask_b32_e64 v6, v10, v6, s[44:45]
	v_cndmask_b32_e64 v7, v11, v7, s[44:45]
	s_waitcnt lgkmcnt(1)
	v_mul_f32_e32 v8, v0, v12
	s_waitcnt lgkmcnt(0)
	v_fma_f32 v5, v16, v5, -v8
	v_fma_f32 v8, -v1, v13, 0
	ds_read_b32 v13, v129 offset:51216
	v_fma_f32 v9, -v2, v14, 0
	v_fma_f32 v12, -v3, v15, 0
	s_waitcnt lgkmcnt(0)
	v_fma_f32 v5, -v4, v13, v5
	v_add_f32_e32 v5, v8, v5
	v_add_f32_e32 v8, v9, v12
	ds_read_b128 v[12:15], v129 offset:51456
	v_add_f32_e32 v5, v8, v5
	s_waitcnt lgkmcnt(0)
	v_mul_f32_e32 v8, v0, v12
	v_fma_f32 v6, v17, v6, -v8
	ds_read_b64 v[8:9], v129 offset:51472
	ds_read_b128 v[16:19], v129 offset:51968
	v_fma_f32 v10, -v1, v13, 0
	v_fma_f32 v12, -v2, v14, 0
	v_fma_f32 v13, -v3, v15, 0
	s_waitcnt lgkmcnt(1)
	v_fma_f32 v6, -v4, v8, v6
	v_fma_f32 v8, -v5, v9, v10
	v_add_f32_e32 v6, v6, v8
	v_add_f32_e32 v8, v12, v13
	v_add_f32_e32 v6, v8, v6
	v_add_u32_e32 v8, 0x600, v69
	ds_read2_b32 v[20:21], v8 offset0:71 offset1:136
	ds_read_b128 v[8:11], v129 offset:51712
	s_waitcnt lgkmcnt(0)
	v_mul_f32_e32 v8, v0, v8
	v_fma_f32 v7, v20, v7, -v8
	v_fma_f32 v12, -v1, v9, 0
	v_fma_f32 v13, -v2, v10, 0
	ds_read_b96 v[8:10], v129 offset:51728
	v_fma_f32 v11, -v3, v11, 0
	v_fma_f32 v20, -v2, v18, 0
	s_waitcnt lgkmcnt(0)
	v_fma_f32 v7, -v4, v8, v7
	v_fma_f32 v8, -v5, v9, v12
	v_fma_f32 v9, -v6, v10, v13
	v_add_f32_e32 v7, v7, v8
	v_add_f32_e32 v8, v11, v9
	v_add_f32_e32 v7, v7, v8
	v_mov_b32_e32 v8, 0x10420
	v_mov_b32_e32 v12, 0x10620
	ds_read_b128 v[8:11], v8
	ds_read_b128 v[12:15], v12
	s_waitcnt lgkmcnt(0)
	v_cndmask_b32_e64 v8, v12, v8, s[44:45]
	v_mul_f32_e32 v12, v0, v16
	v_fma_f32 v8, v21, v8, -v12
	v_fma_f32 v12, -v1, v17, 0
	v_fma_f32 v21, -v3, v19, 0
	ds_read_b128 v[16:19], v129 offset:51984
	v_cndmask_b32_e64 v9, v13, v9, s[44:45]
	v_cndmask_b32_e64 v10, v14, v10, s[44:45]
	v_cndmask_b32_e64 v11, v15, v11, s[44:45]
	s_waitcnt lgkmcnt(0)
	v_fma_f32 v8, -v4, v16, v8
	v_fma_f32 v12, -v5, v17, v12
	v_fma_f32 v16, -v6, v18, v20
	v_fma_f32 v17, -v7, v19, v21
	v_add_f32_e32 v8, v8, v12
	v_add_f32_e32 v12, v16, v17
	v_add_f32_e32 v8, v8, v12
	v_add_u32_e32 v12, 0x800, v69
	ds_read_b128 v[16:19], v129 offset:52224
	ds_read2_b32 v[20:21], v12 offset0:73 offset1:138
	s_waitcnt lgkmcnt(1)
	v_mul_f32_e32 v12, v0, v16
	s_waitcnt lgkmcnt(0)
	v_fma_f32 v9, v20, v9, -v12
	v_fma_f32 v12, -v1, v17, 0
	v_fma_f32 v13, -v2, v18, 0
	v_fma_f32 v20, -v3, v19, 0
	ds_read_b128 v[16:19], v129 offset:52240
	s_waitcnt lgkmcnt(0)
	v_fma_f32 v12, -v5, v17, v12
	ds_read_b32 v17, v129 offset:52256
	v_fma_f32 v9, -v4, v16, v9
	v_fma_f32 v13, -v6, v18, v13
	v_fma_f32 v16, -v7, v19, v20
	s_waitcnt lgkmcnt(0)
	v_fma_f32 v9, -v8, v17, v9
	v_add_f32_e32 v9, v12, v9
	v_add_f32_e32 v12, v13, v16
	ds_read_b128 v[16:19], v129 offset:52480
	v_add_f32_e32 v9, v12, v9
	s_waitcnt lgkmcnt(0)
	v_mul_f32_e32 v12, v0, v16
	v_fma_f32 v10, v21, v10, -v12
	v_fma_f32 v12, -v1, v17, 0
	v_fma_f32 v13, -v2, v18, 0
	v_fma_f32 v14, -v3, v19, 0
	ds_read_b128 v[16:19], v129 offset:52496
	ds_read_b128 v[20:23], v129 offset:52992
	s_waitcnt lgkmcnt(1)
	v_fma_f32 v10, -v4, v16, v10
	v_fma_f32 v16, -v5, v17, v12
	v_fma_f32 v17, -v6, v18, v13
	ds_read_b64 v[12:13], v129 offset:52512
	v_fma_f32 v14, -v7, v19, v14
	s_waitcnt lgkmcnt(0)
	v_fma_f32 v10, -v8, v12, v10
	v_fma_f32 v12, -v9, v13, v16
	v_add_f32_e32 v10, v10, v12
	v_add_f32_e32 v12, v17, v14
	v_add_f32_e32 v10, v12, v10
	v_add_u32_e32 v12, 0xa00, v69
	ds_read2_b32 v[24:25], v12 offset0:75 offset1:140
	ds_read_b128 v[12:15], v129 offset:52736
	s_waitcnt lgkmcnt(0)
	v_mul_f32_e32 v12, v0, v12
	v_fma_f32 v11, v24, v11, -v12
	v_fma_f32 v16, -v1, v13, 0
	v_fma_f32 v17, -v2, v14, 0
	v_fma_f32 v18, -v3, v15, 0
	ds_read_b128 v[12:15], v129 offset:52752
	v_fma_f32 v24, -v2, v22, 0
	s_waitcnt lgkmcnt(0)
	v_fma_f32 v11, -v4, v12, v11
	v_fma_f32 v16, -v5, v13, v16
	v_fma_f32 v17, -v6, v14, v17
	ds_read_b96 v[12:14], v129 offset:52768
	v_fma_f32 v15, -v7, v15, v18
	s_waitcnt lgkmcnt(0)
	v_fma_f32 v11, -v8, v12, v11
	v_fma_f32 v12, -v9, v13, v16
	v_fma_f32 v13, -v10, v14, v17
	v_add_f32_e32 v11, v11, v12
	v_add_f32_e32 v12, v15, v13
	v_add_f32_e32 v11, v11, v12
	v_mov_b32_e32 v12, 0x10430
	v_mov_b32_e32 v16, 0x10630
	ds_read_b128 v[12:15], v12
	ds_read_b128 v[16:19], v16
	s_waitcnt lgkmcnt(0)
	v_cndmask_b32_e64 v12, v16, v12, s[44:45]
	v_mul_f32_e32 v16, v0, v20
	v_fma_f32 v12, v25, v12, -v16
	v_fma_f32 v16, -v1, v21, 0
	v_fma_f32 v25, -v3, v23, 0
	ds_read_b128 v[20:23], v129 offset:53008
	v_cndmask_b32_e64 v13, v17, v13, s[44:45]
	v_cndmask_b32_e64 v14, v18, v14, s[44:45]
	v_cndmask_b32_e64 v15, v19, v15, s[44:45]
	s_waitcnt lgkmcnt(0)
	v_fma_f32 v12, -v4, v20, v12
	v_fma_f32 v16, -v5, v21, v16
	v_fma_f32 v24, -v6, v22, v24
	v_fma_f32 v25, -v7, v23, v25
	ds_read_b128 v[20:23], v129 offset:53024
	s_waitcnt lgkmcnt(0)
	v_fma_f32 v12, -v8, v20, v12
	v_fma_f32 v16, -v9, v21, v16
	v_fma_f32 v20, -v10, v22, v24
	v_fma_f32 v21, -v11, v23, v25
	v_add_f32_e32 v12, v12, v16
	v_add_f32_e32 v16, v20, v21
	v_add_f32_e32 v12, v12, v16
	v_add_u32_e32 v16, 0xc00, v69
	ds_read_b128 v[20:23], v129 offset:53248
	ds_read2_b32 v[24:25], v16 offset0:77 offset1:142
	s_waitcnt lgkmcnt(1)
	v_mul_f32_e32 v16, v0, v20
	s_waitcnt lgkmcnt(0)
	v_fma_f32 v13, v24, v13, -v16
	v_fma_f32 v16, -v1, v21, 0
	v_fma_f32 v17, -v2, v22, 0
	v_fma_f32 v24, -v3, v23, 0
	ds_read_b128 v[20:23], v129 offset:53264
	s_waitcnt lgkmcnt(0)
	v_fma_f32 v13, -v4, v20, v13
	v_fma_f32 v16, -v5, v21, v16
	v_fma_f32 v17, -v6, v22, v17
	v_fma_f32 v24, -v7, v23, v24
	ds_read_b128 v[20:23], v129 offset:53280
	s_waitcnt lgkmcnt(0)
	v_fma_f32 v16, -v9, v21, v16
	ds_read_b32 v21, v129 offset:53296
	v_fma_f32 v13, -v8, v20, v13
	v_fma_f32 v17, -v10, v22, v17
	v_fma_f32 v20, -v11, v23, v24
	s_waitcnt lgkmcnt(0)
	v_fma_f32 v13, -v12, v21, v13
	v_add_f32_e32 v13, v16, v13
	v_add_f32_e32 v16, v17, v20
	ds_read_b128 v[20:23], v129 offset:53504
	v_add_f32_e32 v13, v16, v13
	s_waitcnt lgkmcnt(0)
	v_mul_f32_e32 v16, v0, v20
	v_fma_f32 v14, v25, v14, -v16
	v_fma_f32 v16, -v1, v21, 0
	v_fma_f32 v17, -v2, v22, 0
	v_fma_f32 v18, -v3, v23, 0
	ds_read_b128 v[20:23], v129 offset:53520
	ds_read_b128 v[24:27], v129 offset:54016
	s_waitcnt lgkmcnt(1)
	v_fma_f32 v14, -v4, v20, v14
	v_fma_f32 v16, -v5, v21, v16
	v_fma_f32 v17, -v6, v22, v17
	v_fma_f32 v18, -v7, v23, v18
	ds_read_b128 v[20:23], v129 offset:53536
	s_waitcnt lgkmcnt(0)
	v_fma_f32 v14, -v8, v20, v14
	v_fma_f32 v20, -v9, v21, v16
	v_fma_f32 v21, -v10, v22, v17
	ds_read_b64 v[16:17], v129 offset:53552
	v_fma_f32 v18, -v11, v23, v18
	s_waitcnt lgkmcnt(0)
	v_fma_f32 v14, -v12, v16, v14
	v_fma_f32 v16, -v13, v17, v20
	v_add_f32_e32 v14, v14, v16
	v_add_f32_e32 v16, v21, v18
	v_add_f32_e32 v14, v16, v14
	v_add_u32_e32 v16, 0xe00, v69
	ds_read2_b32 v[28:29], v16 offset0:79 offset1:144
	ds_read_b128 v[16:19], v129 offset:53760
	s_waitcnt lgkmcnt(0)
	v_mul_f32_e32 v16, v0, v16
	v_fma_f32 v15, v28, v15, -v16
	v_fma_f32 v20, -v1, v17, 0
	v_fma_f32 v21, -v2, v18, 0
	v_fma_f32 v22, -v3, v19, 0
	ds_read_b128 v[16:19], v129 offset:53776
	v_fma_f32 v28, -v2, v26, 0
	s_waitcnt lgkmcnt(0)
	v_fma_f32 v15, -v4, v16, v15
	v_fma_f32 v20, -v5, v17, v20
	v_fma_f32 v21, -v6, v18, v21
	v_fma_f32 v22, -v7, v19, v22
	ds_read_b128 v[16:19], v129 offset:53792
	s_waitcnt lgkmcnt(0)
	v_fma_f32 v15, -v8, v16, v15
	v_fma_f32 v20, -v9, v17, v20
	v_fma_f32 v21, -v10, v18, v21
	ds_read_b96 v[16:18], v129 offset:53808
	v_fma_f32 v19, -v11, v19, v22
	s_waitcnt lgkmcnt(0)
	v_fma_f32 v15, -v12, v16, v15
	v_fma_f32 v16, -v13, v17, v20
	v_fma_f32 v17, -v14, v18, v21
	v_add_f32_e32 v15, v15, v16
	v_add_f32_e32 v16, v19, v17
	v_add_f32_e32 v15, v15, v16
	v_mov_b32_e32 v16, 0x10440
	v_mov_b32_e32 v20, 0x10640
	ds_read_b128 v[16:19], v16
	ds_read_b128 v[20:23], v20
	s_waitcnt lgkmcnt(0)
	v_cndmask_b32_e64 v16, v20, v16, s[44:45]
	v_mul_f32_e32 v20, v0, v24
	v_fma_f32 v16, v29, v16, -v20
	v_fma_f32 v20, -v1, v25, 0
	v_fma_f32 v29, -v3, v27, 0
	ds_read_b128 v[24:27], v129 offset:54032
	v_cndmask_b32_e64 v17, v21, v17, s[44:45]
	v_cndmask_b32_e64 v18, v22, v18, s[44:45]
	v_cndmask_b32_e64 v19, v23, v19, s[44:45]
	s_waitcnt lgkmcnt(0)
	v_fma_f32 v16, -v4, v24, v16
	v_fma_f32 v20, -v5, v25, v20
	v_fma_f32 v28, -v6, v26, v28
	v_fma_f32 v29, -v7, v27, v29
	ds_read_b128 v[24:27], v129 offset:54048
	s_waitcnt lgkmcnt(0)
	v_fma_f32 v16, -v8, v24, v16
	v_fma_f32 v20, -v9, v25, v20
	v_fma_f32 v28, -v10, v26, v28
	v_fma_f32 v29, -v11, v27, v29
	ds_read_b128 v[24:27], v129 offset:54064
	s_waitcnt lgkmcnt(0)
	v_fma_f32 v16, -v12, v24, v16
	v_fma_f32 v20, -v13, v25, v20
	v_fma_f32 v24, -v14, v26, v28
	v_fma_f32 v25, -v15, v27, v29
	v_add_f32_e32 v16, v16, v20
	v_add_f32_e32 v20, v24, v25
	v_add_f32_e32 v16, v16, v20
	v_add_u32_e32 v20, 0x1000, v69
	ds_read_b128 v[24:27], v129 offset:54272
	ds_read2_b32 v[28:29], v20 offset0:81 offset1:146
	s_waitcnt lgkmcnt(1)
	v_mul_f32_e32 v20, v0, v24
	s_waitcnt lgkmcnt(0)
	v_fma_f32 v17, v28, v17, -v20
	v_fma_f32 v20, -v1, v25, 0
	v_fma_f32 v21, -v2, v26, 0
	v_fma_f32 v28, -v3, v27, 0
	ds_read_b128 v[100:103], v129 offset:54288
	ds_read_b128 v[24:27], v129 offset:54304
	s_waitcnt lgkmcnt(1)
	v_fma_f32 v17, -v4, v100, v17
	v_fma_f32 v20, -v5, v101, v20
	v_fma_f32 v21, -v6, v102, v21
	v_fma_f32 v28, -v7, v103, v28
	s_waitcnt lgkmcnt(0)
	v_fma_f32 v17, -v8, v24, v17
	v_fma_f32 v20, -v9, v25, v20
	v_fma_f32 v21, -v10, v26, v21
	v_fma_f32 v28, -v11, v27, v28
	ds_read_b128 v[24:27], v129 offset:54320
	s_waitcnt lgkmcnt(0)
	v_fma_f32 v20, -v13, v25, v20
	ds_read_b32 v25, v129 offset:54336
	v_fma_f32 v17, -v12, v24, v17
	v_fma_f32 v21, -v14, v26, v21
	v_fma_f32 v24, -v15, v27, v28
	s_waitcnt lgkmcnt(0)
	v_fma_f32 v17, -v16, v25, v17
	v_add_f32_e32 v17, v20, v17
	v_add_f32_e32 v20, v21, v24
	ds_read_b128 v[24:27], v129 offset:54528
	v_add_f32_e32 v17, v20, v17
	s_waitcnt lgkmcnt(0)
	v_mul_f32_e32 v20, v0, v24
	v_fma_f32 v18, v29, v18, -v20
	v_fma_f32 v20, -v1, v25, 0
	v_fma_f32 v21, -v2, v26, 0
	v_fma_f32 v22, -v3, v27, 0
	ds_read_b128 v[24:27], v129 offset:54544
	ds_read_b128 v[28:31], v129 offset:55040
	s_waitcnt lgkmcnt(1)
	v_fma_f32 v18, -v4, v24, v18
	v_fma_f32 v20, -v5, v25, v20
	v_fma_f32 v21, -v6, v26, v21
	v_fma_f32 v22, -v7, v27, v22
	ds_read_b128 v[24:27], v129 offset:54560
	s_waitcnt lgkmcnt(0)
	v_fma_f32 v18, -v8, v24, v18
	v_fma_f32 v20, -v9, v25, v20
	v_fma_f32 v21, -v10, v26, v21
	v_fma_f32 v22, -v11, v27, v22
	ds_read_b128 v[24:27], v129 offset:54576
	s_waitcnt lgkmcnt(0)
	v_fma_f32 v18, -v12, v24, v18
	v_fma_f32 v24, -v13, v25, v20
	v_fma_f32 v25, -v14, v26, v21
	ds_read_b64 v[20:21], v129 offset:54592
	v_fma_f32 v22, -v15, v27, v22
	s_waitcnt lgkmcnt(0)
	v_fma_f32 v18, -v16, v20, v18
	v_fma_f32 v20, -v17, v21, v24
	v_add_f32_e32 v18, v18, v20
	v_add_f32_e32 v20, v25, v22
	v_add_f32_e32 v18, v20, v18
	v_add_u32_e32 v20, 0x1200, v69
	ds_read2_b32 v[32:33], v20 offset0:83 offset1:148
	ds_read_b128 v[20:23], v129 offset:54784
	s_waitcnt lgkmcnt(0)
	v_mul_f32_e32 v20, v0, v20
	v_fma_f32 v19, v32, v19, -v20
	v_fma_f32 v24, -v1, v21, 0
	v_fma_f32 v25, -v2, v22, 0
	v_fma_f32 v26, -v3, v23, 0
	ds_read_b128 v[20:23], v129 offset:54800
	v_fma_f32 v32, -v2, v30, 0
	s_waitcnt lgkmcnt(0)
	v_fma_f32 v19, -v4, v20, v19
	v_fma_f32 v24, -v5, v21, v24
	v_fma_f32 v25, -v6, v22, v25
	v_fma_f32 v26, -v7, v23, v26
	ds_read_b128 v[20:23], v129 offset:54816
	s_waitcnt lgkmcnt(0)
	v_fma_f32 v19, -v8, v20, v19
	v_fma_f32 v24, -v9, v21, v24
	v_fma_f32 v25, -v10, v22, v25
	v_fma_f32 v26, -v11, v23, v26
	ds_read_b128 v[20:23], v129 offset:54832
	s_waitcnt lgkmcnt(0)
	v_fma_f32 v19, -v12, v20, v19
	v_fma_f32 v24, -v13, v21, v24
	v_fma_f32 v25, -v14, v22, v25
	ds_read_b96 v[20:22], v129 offset:54848
	v_fma_f32 v23, -v15, v23, v26
	s_waitcnt lgkmcnt(0)
	v_fma_f32 v19, -v16, v20, v19
	v_fma_f32 v20, -v17, v21, v24
	v_fma_f32 v21, -v18, v22, v25
	v_add_f32_e32 v19, v19, v20
	v_add_f32_e32 v20, v23, v21
	v_add_f32_e32 v19, v19, v20
	v_mov_b32_e32 v20, 0x10450
	v_mov_b32_e32 v24, 0x10650
	ds_read_b128 v[20:23], v20
	ds_read_b128 v[24:27], v24
	s_waitcnt lgkmcnt(0)
	v_cndmask_b32_e64 v20, v24, v20, s[44:45]
	v_mul_f32_e32 v24, v0, v28
	v_fma_f32 v20, v33, v20, -v24
	v_fma_f32 v24, -v1, v29, 0
	v_fma_f32 v33, -v3, v31, 0
	ds_read_b128 v[28:31], v129 offset:55056
	v_cndmask_b32_e64 v21, v25, v21, s[44:45]
	v_cndmask_b32_e64 v22, v26, v22, s[44:45]
	v_cndmask_b32_e64 v23, v27, v23, s[44:45]
	s_waitcnt lgkmcnt(0)
	v_fma_f32 v20, -v4, v28, v20
	v_fma_f32 v24, -v5, v29, v24
	v_fma_f32 v32, -v6, v30, v32
	v_fma_f32 v33, -v7, v31, v33
	ds_read_b128 v[100:103], v129 offset:55072
	ds_read_b128 v[28:31], v129 offset:55088
	s_waitcnt lgkmcnt(1)
	v_fma_f32 v20, -v8, v100, v20
	v_fma_f32 v24, -v9, v101, v24
	v_fma_f32 v32, -v10, v102, v32
	v_fma_f32 v33, -v11, v103, v33
	s_waitcnt lgkmcnt(0)
	v_fma_f32 v20, -v12, v28, v20
	v_fma_f32 v24, -v13, v29, v24
	v_fma_f32 v32, -v14, v30, v32
	v_fma_f32 v33, -v15, v31, v33
	ds_read_b128 v[28:31], v129 offset:55104
	s_waitcnt lgkmcnt(0)
	v_fma_f32 v20, -v16, v28, v20
	v_fma_f32 v24, -v17, v29, v24
	v_fma_f32 v28, -v18, v30, v32
	v_fma_f32 v29, -v19, v31, v33
	v_add_f32_e32 v20, v20, v24
	v_add_f32_e32 v24, v28, v29
	v_add_f32_e32 v20, v20, v24
	v_add_u32_e32 v24, 0x1400, v69
	ds_read_b128 v[28:31], v129 offset:55296
	ds_read2_b32 v[32:33], v24 offset0:85 offset1:150
	s_waitcnt lgkmcnt(1)
	v_mul_f32_e32 v24, v0, v28
	s_waitcnt lgkmcnt(0)
	v_fma_f32 v21, v32, v21, -v24
	v_fma_f32 v24, -v1, v29, 0
	v_fma_f32 v25, -v2, v30, 0
	v_fma_f32 v32, -v3, v31, 0
	ds_read_b128 v[104:107], v129 offset:55312
	ds_read_b128 v[100:103], v129 offset:55328
	ds_read_b128 v[28:31], v129 offset:55344
	s_waitcnt lgkmcnt(2)
	v_fma_f32 v21, -v4, v104, v21
	v_fma_f32 v24, -v5, v105, v24
	v_fma_f32 v25, -v6, v106, v25
	v_fma_f32 v32, -v7, v107, v32
	s_waitcnt lgkmcnt(1)
	v_fma_f32 v21, -v8, v100, v21
	v_fma_f32 v24, -v9, v101, v24
	v_fma_f32 v25, -v10, v102, v25
	v_fma_f32 v32, -v11, v103, v32
	s_waitcnt lgkmcnt(0)
	v_fma_f32 v21, -v12, v28, v21
	v_fma_f32 v24, -v13, v29, v24
	v_fma_f32 v25, -v14, v30, v25
	v_fma_f32 v32, -v15, v31, v32
	ds_read_b128 v[28:31], v129 offset:55360
	s_waitcnt lgkmcnt(0)
	v_fma_f32 v24, -v17, v29, v24
	ds_read_b32 v29, v129 offset:55376
	v_fma_f32 v21, -v16, v28, v21
	v_fma_f32 v25, -v18, v30, v25
	v_fma_f32 v28, -v19, v31, v32
	s_waitcnt lgkmcnt(0)
	v_fma_f32 v21, -v20, v29, v21
	v_add_f32_e32 v21, v24, v21
	v_add_f32_e32 v24, v25, v28
	ds_read_b128 v[28:31], v129 offset:55552
	v_add_f32_e32 v21, v24, v21
	s_waitcnt lgkmcnt(0)
	v_mul_f32_e32 v24, v0, v28
	v_fma_f32 v22, v33, v22, -v24
	v_fma_f32 v24, -v1, v29, 0
	v_fma_f32 v25, -v2, v30, 0
	v_fma_f32 v26, -v3, v31, 0
	ds_read_b128 v[28:31], v129 offset:55568
	ds_read_b128 v[32:35], v129 offset:56064
	s_waitcnt lgkmcnt(1)
	v_fma_f32 v22, -v4, v28, v22
	v_fma_f32 v24, -v5, v29, v24
	v_fma_f32 v25, -v6, v30, v25
	v_fma_f32 v26, -v7, v31, v26
	ds_read_b128 v[100:103], v129 offset:55584
	ds_read_b128 v[28:31], v129 offset:55600
	s_waitcnt lgkmcnt(1)
	v_fma_f32 v22, -v8, v100, v22
	v_fma_f32 v24, -v9, v101, v24
	v_fma_f32 v25, -v10, v102, v25
	v_fma_f32 v26, -v11, v103, v26
	s_waitcnt lgkmcnt(0)
	v_fma_f32 v22, -v12, v28, v22
	v_fma_f32 v24, -v13, v29, v24
	v_fma_f32 v25, -v14, v30, v25
	v_fma_f32 v26, -v15, v31, v26
	ds_read_b128 v[28:31], v129 offset:55616
	s_waitcnt lgkmcnt(0)
	v_fma_f32 v22, -v16, v28, v22
	v_fma_f32 v28, -v17, v29, v24
	v_fma_f32 v29, -v18, v30, v25
	ds_read_b64 v[24:25], v129 offset:55632
	v_fma_f32 v26, -v19, v31, v26
	s_waitcnt lgkmcnt(0)
	v_fma_f32 v22, -v20, v24, v22
	v_fma_f32 v24, -v21, v25, v28
	v_add_f32_e32 v22, v22, v24
	v_add_f32_e32 v24, v29, v26
	v_add_f32_e32 v22, v24, v22
	v_add_u32_e32 v24, 0x1600, v69
	ds_read2_b32 v[36:37], v24 offset0:87 offset1:152
	ds_read_b128 v[24:27], v129 offset:55808
	s_waitcnt lgkmcnt(0)
	v_mul_f32_e32 v24, v0, v24
	v_fma_f32 v23, v36, v23, -v24
	v_fma_f32 v28, -v1, v25, 0
	v_fma_f32 v29, -v2, v26, 0
	v_fma_f32 v30, -v3, v27, 0
	ds_read_b128 v[24:27], v129 offset:55824
	v_fma_f32 v36, -v2, v34, 0
	s_waitcnt lgkmcnt(0)
	v_fma_f32 v23, -v4, v24, v23
	v_fma_f32 v28, -v5, v25, v28
	v_fma_f32 v29, -v6, v26, v29
	v_fma_f32 v30, -v7, v27, v30
	ds_read_b128 v[100:103], v129 offset:55840
	ds_read_b128 v[24:27], v129 offset:55856
	s_waitcnt lgkmcnt(1)
	v_fma_f32 v23, -v8, v100, v23
	v_fma_f32 v28, -v9, v101, v28
	v_fma_f32 v29, -v10, v102, v29
	v_fma_f32 v30, -v11, v103, v30
	s_waitcnt lgkmcnt(0)
	v_fma_f32 v23, -v12, v24, v23
	v_fma_f32 v28, -v13, v25, v28
	v_fma_f32 v29, -v14, v26, v29
	v_fma_f32 v30, -v15, v27, v30
	ds_read_b128 v[24:27], v129 offset:55872
	s_waitcnt lgkmcnt(0)
	v_fma_f32 v23, -v16, v24, v23
	v_fma_f32 v28, -v17, v25, v28
	v_fma_f32 v29, -v18, v26, v29
	ds_read_b96 v[24:26], v129 offset:55888
	v_fma_f32 v27, -v19, v27, v30
	s_waitcnt lgkmcnt(0)
	v_fma_f32 v23, -v20, v24, v23
	v_fma_f32 v24, -v21, v25, v28
	v_fma_f32 v25, -v22, v26, v29
	v_add_f32_e32 v23, v23, v24
	v_add_f32_e32 v24, v27, v25
	v_add_f32_e32 v23, v23, v24
	v_mov_b32_e32 v24, 0x10460
	v_mov_b32_e32 v28, 0x10660
	ds_read_b128 v[24:27], v24
	ds_read_b128 v[28:31], v28
	s_waitcnt lgkmcnt(0)
	v_cndmask_b32_e64 v24, v28, v24, s[44:45]
	v_mul_f32_e32 v28, v0, v32
	v_fma_f32 v24, v37, v24, -v28
	v_fma_f32 v28, -v1, v33, 0
	v_fma_f32 v37, -v3, v35, 0
	ds_read_b128 v[32:35], v129 offset:56080
	v_cndmask_b32_e64 v25, v29, v25, s[44:45]
	v_cndmask_b32_e64 v26, v30, v26, s[44:45]
	v_cndmask_b32_e64 v27, v31, v27, s[44:45]
	s_waitcnt lgkmcnt(0)
	v_fma_f32 v24, -v4, v32, v24
	v_fma_f32 v28, -v5, v33, v28
	v_fma_f32 v36, -v6, v34, v36
	v_fma_f32 v37, -v7, v35, v37
	ds_read_b128 v[104:107], v129 offset:56096
	ds_read_b128 v[100:103], v129 offset:56112
	ds_read_b128 v[32:35], v129 offset:56128
	s_waitcnt lgkmcnt(2)
	v_fma_f32 v24, -v8, v104, v24
	v_fma_f32 v28, -v9, v105, v28
	v_fma_f32 v36, -v10, v106, v36
	v_fma_f32 v37, -v11, v107, v37
	s_waitcnt lgkmcnt(1)
	v_fma_f32 v24, -v12, v100, v24
	v_fma_f32 v28, -v13, v101, v28
	v_fma_f32 v36, -v14, v102, v36
	v_fma_f32 v37, -v15, v103, v37
	s_waitcnt lgkmcnt(0)
	v_fma_f32 v24, -v16, v32, v24
	v_fma_f32 v28, -v17, v33, v28
	v_fma_f32 v36, -v18, v34, v36
	v_fma_f32 v37, -v19, v35, v37
	ds_read_b128 v[32:35], v129 offset:56144
	s_waitcnt lgkmcnt(0)
	v_fma_f32 v24, -v20, v32, v24
	v_fma_f32 v28, -v21, v33, v28
	v_fma_f32 v32, -v22, v34, v36
	v_fma_f32 v33, -v23, v35, v37
	v_add_f32_e32 v24, v24, v28
	v_add_f32_e32 v28, v32, v33
	v_add_f32_e32 v24, v24, v28
	v_add_u32_e32 v28, 0x1800, v69
	ds_read_b128 v[32:35], v129 offset:56320
	ds_read2_b32 v[36:37], v28 offset0:89 offset1:154
	s_waitcnt lgkmcnt(1)
	v_mul_f32_e32 v28, v0, v32
	s_waitcnt lgkmcnt(0)
	v_fma_f32 v25, v36, v25, -v28
	v_fma_f32 v28, -v1, v33, 0
	v_fma_f32 v29, -v2, v34, 0
	v_fma_f32 v36, -v3, v35, 0
	ds_read_b128 v[108:111], v129 offset:56336
	ds_read_b128 v[104:107], v129 offset:56352
	ds_read_b128 v[100:103], v129 offset:56368
	ds_read_b128 v[32:35], v129 offset:56384
	s_waitcnt lgkmcnt(3)
	v_fma_f32 v25, -v4, v108, v25
	v_fma_f32 v28, -v5, v109, v28
	v_fma_f32 v29, -v6, v110, v29
	v_fma_f32 v36, -v7, v111, v36
	s_waitcnt lgkmcnt(2)
	v_fma_f32 v25, -v8, v104, v25
	v_fma_f32 v28, -v9, v105, v28
	v_fma_f32 v29, -v10, v106, v29
	v_fma_f32 v36, -v11, v107, v36
	s_waitcnt lgkmcnt(1)
	v_fma_f32 v25, -v12, v100, v25
	v_fma_f32 v28, -v13, v101, v28
	v_fma_f32 v29, -v14, v102, v29
	v_fma_f32 v36, -v15, v103, v36
	s_waitcnt lgkmcnt(0)
	v_fma_f32 v25, -v16, v32, v25
	v_fma_f32 v28, -v17, v33, v28
	v_fma_f32 v29, -v18, v34, v29
	v_fma_f32 v36, -v19, v35, v36
	ds_read_b128 v[32:35], v129 offset:56400
	s_waitcnt lgkmcnt(0)
	v_fma_f32 v28, -v21, v33, v28
	ds_read_b32 v33, v129 offset:56416
	v_fma_f32 v25, -v20, v32, v25
	v_fma_f32 v29, -v22, v34, v29
	v_fma_f32 v32, -v23, v35, v36
	s_waitcnt lgkmcnt(0)
	v_fma_f32 v25, -v24, v33, v25
	v_add_f32_e32 v25, v28, v25
	v_add_f32_e32 v28, v29, v32
	ds_read_b128 v[32:35], v129 offset:56576
	v_add_f32_e32 v25, v28, v25
	s_waitcnt lgkmcnt(0)
	v_mul_f32_e32 v28, v0, v32
	v_fma_f32 v26, v37, v26, -v28
	v_fma_f32 v28, -v1, v33, 0
	v_fma_f32 v29, -v2, v34, 0
	v_fma_f32 v30, -v3, v35, 0
	ds_read_b128 v[32:35], v129 offset:56592
	ds_read_b128 v[36:39], v129 offset:57088
	s_waitcnt lgkmcnt(1)
	v_fma_f32 v26, -v4, v32, v26
	v_fma_f32 v28, -v5, v33, v28
	v_fma_f32 v29, -v6, v34, v29
	v_fma_f32 v30, -v7, v35, v30
	ds_read_b128 v[104:107], v129 offset:56608
	ds_read_b128 v[100:103], v129 offset:56624
	ds_read_b128 v[32:35], v129 offset:56640
	s_waitcnt lgkmcnt(2)
	v_fma_f32 v26, -v8, v104, v26
	v_fma_f32 v28, -v9, v105, v28
	v_fma_f32 v29, -v10, v106, v29
	v_fma_f32 v30, -v11, v107, v30
	s_waitcnt lgkmcnt(1)
	v_fma_f32 v26, -v12, v100, v26
	v_fma_f32 v28, -v13, v101, v28
	v_fma_f32 v29, -v14, v102, v29
	v_fma_f32 v30, -v15, v103, v30
	s_waitcnt lgkmcnt(0)
	v_fma_f32 v26, -v16, v32, v26
	v_fma_f32 v28, -v17, v33, v28
	v_fma_f32 v29, -v18, v34, v29
	v_fma_f32 v30, -v19, v35, v30
	ds_read_b128 v[32:35], v129 offset:56656
	s_waitcnt lgkmcnt(0)
	v_fma_f32 v26, -v20, v32, v26
	v_fma_f32 v32, -v21, v33, v28
	v_fma_f32 v33, -v22, v34, v29
	ds_read_b64 v[28:29], v129 offset:56672
	v_fma_f32 v30, -v23, v35, v30
	s_waitcnt lgkmcnt(0)
	v_fma_f32 v26, -v24, v28, v26
	v_fma_f32 v28, -v25, v29, v32
	v_add_f32_e32 v26, v26, v28
	v_add_f32_e32 v28, v33, v30
	v_add_f32_e32 v26, v28, v26
	v_add_u32_e32 v28, 0x1a00, v69
	ds_read2_b32 v[40:41], v28 offset0:91 offset1:156
	ds_read_b128 v[28:31], v129 offset:56832
	s_waitcnt lgkmcnt(0)
	v_mul_f32_e32 v28, v0, v28
	v_fma_f32 v27, v40, v27, -v28
	v_fma_f32 v32, -v1, v29, 0
	v_fma_f32 v33, -v2, v30, 0
	v_fma_f32 v34, -v3, v31, 0
	ds_read_b128 v[28:31], v129 offset:56848
	v_fma_f32 v40, -v2, v38, 0
	s_waitcnt lgkmcnt(0)
	v_fma_f32 v27, -v4, v28, v27
	v_fma_f32 v32, -v5, v29, v32
	v_fma_f32 v33, -v6, v30, v33
	v_fma_f32 v34, -v7, v31, v34
	ds_read_b128 v[104:107], v129 offset:56864
	ds_read_b128 v[100:103], v129 offset:56880
	ds_read_b128 v[28:31], v129 offset:56896
	s_waitcnt lgkmcnt(2)
	v_fma_f32 v27, -v8, v104, v27
	v_fma_f32 v32, -v9, v105, v32
	v_fma_f32 v33, -v10, v106, v33
	v_fma_f32 v34, -v11, v107, v34
	s_waitcnt lgkmcnt(1)
	v_fma_f32 v27, -v12, v100, v27
	v_fma_f32 v32, -v13, v101, v32
	v_fma_f32 v33, -v14, v102, v33
	v_fma_f32 v34, -v15, v103, v34
	s_waitcnt lgkmcnt(0)
	v_fma_f32 v27, -v16, v28, v27
	v_fma_f32 v32, -v17, v29, v32
	v_fma_f32 v33, -v18, v30, v33
	v_fma_f32 v34, -v19, v31, v34
	ds_read_b128 v[28:31], v129 offset:56912
	s_waitcnt lgkmcnt(0)
	v_fma_f32 v27, -v20, v28, v27
	v_fma_f32 v32, -v21, v29, v32
	v_fma_f32 v33, -v22, v30, v33
	ds_read_b96 v[28:30], v129 offset:56928
	v_fma_f32 v31, -v23, v31, v34
	s_waitcnt lgkmcnt(0)
	v_fma_f32 v27, -v24, v28, v27
	v_fma_f32 v28, -v25, v29, v32
	v_fma_f32 v29, -v26, v30, v33
	v_add_f32_e32 v27, v27, v28
	v_add_f32_e32 v28, v31, v29
	v_add_f32_e32 v27, v27, v28
	v_mov_b32_e32 v28, 0x10470
	v_mov_b32_e32 v32, 0x10670
	ds_read_b128 v[28:31], v28
	ds_read_b128 v[32:35], v32
	s_waitcnt lgkmcnt(0)
	v_cndmask_b32_e64 v28, v32, v28, s[44:45]
	v_mul_f32_e32 v32, v0, v36
	v_fma_f32 v28, v41, v28, -v32
	v_fma_f32 v32, -v1, v37, 0
	v_fma_f32 v41, -v3, v39, 0
	ds_read_b128 v[36:39], v129 offset:57104
	v_cndmask_b32_e64 v29, v33, v29, s[44:45]
	v_cndmask_b32_e64 v30, v34, v30, s[44:45]
	v_cndmask_b32_e64 v31, v35, v31, s[44:45]
	s_waitcnt lgkmcnt(0)
	v_fma_f32 v28, -v4, v36, v28
	v_fma_f32 v32, -v5, v37, v32
	v_fma_f32 v40, -v6, v38, v40
	v_fma_f32 v41, -v7, v39, v41
	ds_read_b128 v[108:111], v129 offset:57120
	ds_read_b128 v[104:107], v129 offset:57136
	ds_read_b128 v[100:103], v129 offset:57152
	ds_read_b128 v[36:39], v129 offset:57168
	s_waitcnt lgkmcnt(3)
	v_fma_f32 v28, -v8, v108, v28
	v_fma_f32 v32, -v9, v109, v32
	v_fma_f32 v40, -v10, v110, v40
	v_fma_f32 v41, -v11, v111, v41
	s_waitcnt lgkmcnt(2)
	v_fma_f32 v28, -v12, v104, v28
	v_fma_f32 v32, -v13, v105, v32
	v_fma_f32 v40, -v14, v106, v40
	v_fma_f32 v41, -v15, v107, v41
	s_waitcnt lgkmcnt(1)
	v_fma_f32 v28, -v16, v100, v28
	v_fma_f32 v32, -v17, v101, v32
	v_fma_f32 v40, -v18, v102, v40
	v_fma_f32 v41, -v19, v103, v41
	s_waitcnt lgkmcnt(0)
	v_fma_f32 v28, -v20, v36, v28
	v_fma_f32 v32, -v21, v37, v32
	v_fma_f32 v40, -v22, v38, v40
	v_fma_f32 v41, -v23, v39, v41
	ds_read_b128 v[36:39], v129 offset:57184
	s_waitcnt lgkmcnt(0)
	v_fma_f32 v28, -v24, v36, v28
	v_fma_f32 v32, -v25, v37, v32
	v_fma_f32 v36, -v26, v38, v40
	v_fma_f32 v37, -v27, v39, v41
	v_add_f32_e32 v28, v28, v32
	v_add_f32_e32 v32, v36, v37
	v_add_f32_e32 v28, v28, v32
	v_add_u32_e32 v32, 0x1c00, v69
	ds_read_b128 v[36:39], v129 offset:57344
	ds_read2_b32 v[40:41], v32 offset0:93 offset1:158
	s_waitcnt lgkmcnt(1)
	v_mul_f32_e32 v32, v0, v36
	s_waitcnt lgkmcnt(0)
	v_fma_f32 v29, v40, v29, -v32
	v_fma_f32 v32, -v1, v37, 0
	v_fma_f32 v33, -v2, v38, 0
	v_fma_f32 v40, -v3, v39, 0
	ds_read_b128 v[112:115], v129 offset:57360
	ds_read_b128 v[108:111], v129 offset:57376
	ds_read_b128 v[104:107], v129 offset:57392
	ds_read_b128 v[100:103], v129 offset:57408
	ds_read_b128 v[36:39], v129 offset:57424
	s_waitcnt lgkmcnt(4)
	v_fma_f32 v29, -v4, v112, v29
	v_fma_f32 v32, -v5, v113, v32
	v_fma_f32 v33, -v6, v114, v33
	v_fma_f32 v40, -v7, v115, v40
	s_waitcnt lgkmcnt(3)
	v_fma_f32 v29, -v8, v108, v29
	v_fma_f32 v32, -v9, v109, v32
	v_fma_f32 v33, -v10, v110, v33
	v_fma_f32 v40, -v11, v111, v40
	s_waitcnt lgkmcnt(2)
	v_fma_f32 v29, -v12, v104, v29
	v_fma_f32 v32, -v13, v105, v32
	v_fma_f32 v33, -v14, v106, v33
	v_fma_f32 v40, -v15, v107, v40
	s_waitcnt lgkmcnt(1)
	v_fma_f32 v29, -v16, v100, v29
	v_fma_f32 v32, -v17, v101, v32
	v_fma_f32 v33, -v18, v102, v33
	v_fma_f32 v40, -v19, v103, v40
	s_waitcnt lgkmcnt(0)
	v_fma_f32 v29, -v20, v36, v29
	v_fma_f32 v32, -v21, v37, v32
	v_fma_f32 v33, -v22, v38, v33
	v_fma_f32 v40, -v23, v39, v40
	ds_read_b128 v[36:39], v129 offset:57440
	s_waitcnt lgkmcnt(0)
	v_fma_f32 v32, -v25, v37, v32
	ds_read_b32 v37, v129 offset:57456
	v_fma_f32 v29, -v24, v36, v29
	v_fma_f32 v33, -v26, v38, v33
	v_fma_f32 v36, -v27, v39, v40
	s_waitcnt lgkmcnt(0)
	v_fma_f32 v29, -v28, v37, v29
	v_add_f32_e32 v29, v32, v29
	v_add_f32_e32 v32, v33, v36
	ds_read_b128 v[36:39], v129 offset:57600
	v_add_f32_e32 v29, v32, v29
	s_waitcnt lgkmcnt(0)
	v_mul_f32_e32 v32, v0, v36
	v_fma_f32 v30, v41, v30, -v32
	v_fma_f32 v32, -v1, v37, 0
	v_fma_f32 v33, -v2, v38, 0
	v_fma_f32 v34, -v3, v39, 0
	ds_read_b128 v[36:39], v129 offset:57616
	ds_read_b128 v[40:43], v129 offset:58112
	s_waitcnt lgkmcnt(1)
	v_fma_f32 v30, -v4, v36, v30
	v_fma_f32 v32, -v5, v37, v32
	v_fma_f32 v33, -v6, v38, v33
	v_fma_f32 v34, -v7, v39, v34
	ds_read_b128 v[108:111], v129 offset:57632
	ds_read_b128 v[104:107], v129 offset:57648
	ds_read_b128 v[100:103], v129 offset:57664
	ds_read_b128 v[36:39], v129 offset:57680
	s_waitcnt lgkmcnt(3)
	v_fma_f32 v30, -v8, v108, v30
	v_fma_f32 v32, -v9, v109, v32
	v_fma_f32 v33, -v10, v110, v33
	v_fma_f32 v34, -v11, v111, v34
	s_waitcnt lgkmcnt(2)
	v_fma_f32 v30, -v12, v104, v30
	v_fma_f32 v32, -v13, v105, v32
	v_fma_f32 v33, -v14, v106, v33
	v_fma_f32 v34, -v15, v107, v34
	s_waitcnt lgkmcnt(1)
	v_fma_f32 v30, -v16, v100, v30
	v_fma_f32 v32, -v17, v101, v32
	v_fma_f32 v33, -v18, v102, v33
	v_fma_f32 v34, -v19, v103, v34
	s_waitcnt lgkmcnt(0)
	v_fma_f32 v30, -v20, v36, v30
	v_fma_f32 v32, -v21, v37, v32
	v_fma_f32 v33, -v22, v38, v33
	v_fma_f32 v34, -v23, v39, v34
	ds_read_b128 v[36:39], v129 offset:57696
	s_waitcnt lgkmcnt(0)
	v_fma_f32 v30, -v24, v36, v30
	v_fma_f32 v36, -v25, v37, v32
	v_fma_f32 v37, -v26, v38, v33
	ds_read_b64 v[32:33], v129 offset:57712
	v_fma_f32 v34, -v27, v39, v34
	s_waitcnt lgkmcnt(0)
	v_fma_f32 v30, -v28, v32, v30
	v_fma_f32 v32, -v29, v33, v36
	v_add_f32_e32 v30, v30, v32
	v_add_f32_e32 v32, v37, v34
	v_add_f32_e32 v30, v32, v30
	v_add_u32_e32 v32, 0x1e00, v69
	ds_read2_b32 v[44:45], v32 offset0:95 offset1:160
	ds_read_b128 v[32:35], v129 offset:57856
	s_waitcnt lgkmcnt(0)
	v_mul_f32_e32 v32, v0, v32
	v_fma_f32 v31, v44, v31, -v32
	v_fma_f32 v36, -v1, v33, 0
	v_fma_f32 v37, -v2, v34, 0
	v_fma_f32 v38, -v3, v35, 0
	ds_read_b128 v[32:35], v129 offset:57872
	v_fma_f32 v44, -v2, v42, 0
	s_waitcnt lgkmcnt(0)
	v_fma_f32 v31, -v4, v32, v31
	v_fma_f32 v36, -v5, v33, v36
	v_fma_f32 v37, -v6, v34, v37
	v_fma_f32 v38, -v7, v35, v38
	ds_read_b128 v[108:111], v129 offset:57888
	ds_read_b128 v[104:107], v129 offset:57904
	ds_read_b128 v[100:103], v129 offset:57920
	ds_read_b128 v[32:35], v129 offset:57936
	s_waitcnt lgkmcnt(3)
	v_fma_f32 v31, -v8, v108, v31
	v_fma_f32 v36, -v9, v109, v36
	v_fma_f32 v37, -v10, v110, v37
	v_fma_f32 v38, -v11, v111, v38
	s_waitcnt lgkmcnt(2)
	v_fma_f32 v31, -v12, v104, v31
	v_fma_f32 v36, -v13, v105, v36
	v_fma_f32 v37, -v14, v106, v37
	v_fma_f32 v38, -v15, v107, v38
	s_waitcnt lgkmcnt(1)
	v_fma_f32 v31, -v16, v100, v31
	v_fma_f32 v36, -v17, v101, v36
	v_fma_f32 v37, -v18, v102, v37
	v_fma_f32 v38, -v19, v103, v38
	s_waitcnt lgkmcnt(0)
	v_fma_f32 v31, -v20, v32, v31
	v_fma_f32 v36, -v21, v33, v36
	v_fma_f32 v37, -v22, v34, v37
	v_fma_f32 v38, -v23, v35, v38
	ds_read_b128 v[32:35], v129 offset:57952
	s_waitcnt lgkmcnt(0)
	v_fma_f32 v31, -v24, v32, v31
	v_fma_f32 v36, -v25, v33, v36
	v_fma_f32 v37, -v26, v34, v37
	ds_read_b96 v[32:34], v129 offset:57968
	v_fma_f32 v35, -v27, v35, v38
	s_waitcnt lgkmcnt(0)
	v_fma_f32 v31, -v28, v32, v31
	v_fma_f32 v32, -v29, v33, v36
	v_fma_f32 v33, -v30, v34, v37
	v_add_f32_e32 v31, v31, v32
	v_add_f32_e32 v32, v35, v33
	v_add_f32_e32 v31, v31, v32
	v_mov_b32_e32 v32, 0x10480
	v_mov_b32_e32 v36, 0x10680
	ds_read_b128 v[32:35], v32
	ds_read_b128 v[36:39], v36
	s_waitcnt lgkmcnt(0)
	v_cndmask_b32_e64 v32, v36, v32, s[44:45]
	v_mul_f32_e32 v36, v0, v40
	v_fma_f32 v32, v45, v32, -v36
	v_fma_f32 v36, -v1, v41, 0
	v_fma_f32 v45, -v3, v43, 0
	ds_read_b128 v[40:43], v129 offset:58128
	v_cndmask_b32_e64 v33, v37, v33, s[44:45]
	v_cndmask_b32_e64 v34, v38, v34, s[44:45]
	v_cndmask_b32_e64 v35, v39, v35, s[44:45]
	s_waitcnt lgkmcnt(0)
	v_fma_f32 v32, -v4, v40, v32
	v_fma_f32 v36, -v5, v41, v36
	v_fma_f32 v44, -v6, v42, v44
	v_fma_f32 v45, -v7, v43, v45
	ds_read_b128 v[112:115], v129 offset:58144
	ds_read_b128 v[108:111], v129 offset:58160
	ds_read_b128 v[104:107], v129 offset:58176
	ds_read_b128 v[100:103], v129 offset:58192
	ds_read_b128 v[40:43], v129 offset:58208
	s_waitcnt lgkmcnt(4)
	v_fma_f32 v32, -v8, v112, v32
	v_fma_f32 v36, -v9, v113, v36
	v_fma_f32 v44, -v10, v114, v44
	v_fma_f32 v45, -v11, v115, v45
	s_waitcnt lgkmcnt(3)
	v_fma_f32 v32, -v12, v108, v32
	v_fma_f32 v36, -v13, v109, v36
	v_fma_f32 v44, -v14, v110, v44
	v_fma_f32 v45, -v15, v111, v45
	s_waitcnt lgkmcnt(2)
	v_fma_f32 v32, -v16, v104, v32
	v_fma_f32 v36, -v17, v105, v36
	v_fma_f32 v44, -v18, v106, v44
	v_fma_f32 v45, -v19, v107, v45
	s_waitcnt lgkmcnt(1)
	v_fma_f32 v32, -v20, v100, v32
	v_fma_f32 v36, -v21, v101, v36
	v_fma_f32 v44, -v22, v102, v44
	v_fma_f32 v45, -v23, v103, v45
	s_waitcnt lgkmcnt(0)
	v_fma_f32 v32, -v24, v40, v32
	v_fma_f32 v36, -v25, v41, v36
	v_fma_f32 v44, -v26, v42, v44
	v_fma_f32 v45, -v27, v43, v45
	ds_read_b128 v[40:43], v129 offset:58224
	s_waitcnt lgkmcnt(0)
	v_fma_f32 v32, -v28, v40, v32
	v_fma_f32 v36, -v29, v41, v36
	v_fma_f32 v40, -v30, v42, v44
	v_fma_f32 v41, -v31, v43, v45
	v_add_f32_e32 v32, v32, v36
	v_add_f32_e32 v36, v40, v41
	v_add_f32_e32 v32, v32, v36
	v_add_u32_e32 v36, 0x2000, v69
	ds_read_b128 v[40:43], v129 offset:58368
	ds_read2_b32 v[44:45], v36 offset0:97 offset1:162
	s_waitcnt lgkmcnt(1)
	v_mul_f32_e32 v36, v0, v40
	s_waitcnt lgkmcnt(0)
	v_fma_f32 v33, v44, v33, -v36
	v_fma_f32 v36, -v1, v41, 0
	v_fma_f32 v37, -v2, v42, 0
	v_fma_f32 v44, -v3, v43, 0
	ds_read_b128 v[116:119], v129 offset:58384
	ds_read_b128 v[112:115], v129 offset:58400
	ds_read_b128 v[108:111], v129 offset:58416
	ds_read_b128 v[104:107], v129 offset:58432
	ds_read_b128 v[100:103], v129 offset:58448
	ds_read_b128 v[40:43], v129 offset:58464
	s_waitcnt lgkmcnt(5)
	v_fma_f32 v33, -v4, v116, v33
	v_fma_f32 v36, -v5, v117, v36
	v_fma_f32 v37, -v6, v118, v37
	v_fma_f32 v44, -v7, v119, v44
	s_waitcnt lgkmcnt(4)
	v_fma_f32 v33, -v8, v112, v33
	v_fma_f32 v36, -v9, v113, v36
	v_fma_f32 v37, -v10, v114, v37
	v_fma_f32 v44, -v11, v115, v44
	s_waitcnt lgkmcnt(3)
	v_fma_f32 v33, -v12, v108, v33
	v_fma_f32 v36, -v13, v109, v36
	v_fma_f32 v37, -v14, v110, v37
	v_fma_f32 v44, -v15, v111, v44
	s_waitcnt lgkmcnt(2)
	v_fma_f32 v33, -v16, v104, v33
	v_fma_f32 v36, -v17, v105, v36
	v_fma_f32 v37, -v18, v106, v37
	v_fma_f32 v44, -v19, v107, v44
	s_waitcnt lgkmcnt(1)
	v_fma_f32 v33, -v20, v100, v33
	v_fma_f32 v36, -v21, v101, v36
	v_fma_f32 v37, -v22, v102, v37
	v_fma_f32 v44, -v23, v103, v44
	s_waitcnt lgkmcnt(0)
	v_fma_f32 v33, -v24, v40, v33
	v_fma_f32 v36, -v25, v41, v36
	v_fma_f32 v37, -v26, v42, v37
	v_fma_f32 v44, -v27, v43, v44
	ds_read_b128 v[40:43], v129 offset:58480
	s_waitcnt lgkmcnt(0)
	v_fma_f32 v36, -v29, v41, v36
	ds_read_b32 v41, v129 offset:58496
	v_fma_f32 v33, -v28, v40, v33
	v_fma_f32 v37, -v30, v42, v37
	v_fma_f32 v40, -v31, v43, v44
	s_waitcnt lgkmcnt(0)
	v_fma_f32 v33, -v32, v41, v33
	v_add_f32_e32 v33, v36, v33
	v_add_f32_e32 v36, v37, v40
	ds_read_b128 v[40:43], v129 offset:58624
	v_add_f32_e32 v33, v36, v33
	s_waitcnt lgkmcnt(0)
	v_mul_f32_e32 v36, v0, v40
	v_fma_f32 v34, v45, v34, -v36
	v_fma_f32 v36, -v1, v41, 0
	v_fma_f32 v37, -v2, v42, 0
	v_fma_f32 v38, -v3, v43, 0
	ds_read_b128 v[40:43], v129 offset:58640
	ds_read_b128 v[44:47], v129 offset:59136
	s_waitcnt lgkmcnt(1)
	v_fma_f32 v34, -v4, v40, v34
	v_fma_f32 v36, -v5, v41, v36
	v_fma_f32 v37, -v6, v42, v37
	v_fma_f32 v38, -v7, v43, v38
	ds_read_b128 v[112:115], v129 offset:58656
	ds_read_b128 v[108:111], v129 offset:58672
	ds_read_b128 v[104:107], v129 offset:58688
	ds_read_b128 v[100:103], v129 offset:58704
	ds_read_b128 v[40:43], v129 offset:58720
	s_waitcnt lgkmcnt(4)
	v_fma_f32 v34, -v8, v112, v34
	v_fma_f32 v36, -v9, v113, v36
	v_fma_f32 v37, -v10, v114, v37
	v_fma_f32 v38, -v11, v115, v38
	s_waitcnt lgkmcnt(3)
	v_fma_f32 v34, -v12, v108, v34
	v_fma_f32 v36, -v13, v109, v36
	v_fma_f32 v37, -v14, v110, v37
	v_fma_f32 v38, -v15, v111, v38
	s_waitcnt lgkmcnt(2)
	v_fma_f32 v34, -v16, v104, v34
	v_fma_f32 v36, -v17, v105, v36
	v_fma_f32 v37, -v18, v106, v37
	v_fma_f32 v38, -v19, v107, v38
	s_waitcnt lgkmcnt(1)
	v_fma_f32 v34, -v20, v100, v34
	v_fma_f32 v36, -v21, v101, v36
	v_fma_f32 v37, -v22, v102, v37
	v_fma_f32 v38, -v23, v103, v38
	s_waitcnt lgkmcnt(0)
	v_fma_f32 v34, -v24, v40, v34
	v_fma_f32 v36, -v25, v41, v36
	v_fma_f32 v37, -v26, v42, v37
	v_fma_f32 v38, -v27, v43, v38
	ds_read_b128 v[40:43], v129 offset:58736
	s_waitcnt lgkmcnt(0)
	v_fma_f32 v34, -v28, v40, v34
	v_fma_f32 v40, -v29, v41, v36
	v_fma_f32 v41, -v30, v42, v37
	ds_read_b64 v[36:37], v129 offset:58752
	v_fma_f32 v38, -v31, v43, v38
	s_waitcnt lgkmcnt(0)
	v_fma_f32 v34, -v32, v36, v34
	v_fma_f32 v36, -v33, v37, v40
	v_add_f32_e32 v34, v34, v36
	v_add_f32_e32 v36, v41, v38
	v_add_f32_e32 v34, v36, v34
	v_add_u32_e32 v36, 0x2200, v69
	ds_read2_b32 v[48:49], v36 offset0:99 offset1:164
	ds_read_b128 v[36:39], v129 offset:58880
	s_waitcnt lgkmcnt(0)
	v_mul_f32_e32 v36, v0, v36
	v_fma_f32 v35, v48, v35, -v36
	v_fma_f32 v40, -v1, v37, 0
	v_fma_f32 v41, -v2, v38, 0
	v_fma_f32 v42, -v3, v39, 0
	ds_read_b128 v[36:39], v129 offset:58896
	v_fma_f32 v48, -v2, v46, 0
	s_waitcnt lgkmcnt(0)
	v_fma_f32 v35, -v4, v36, v35
	v_fma_f32 v40, -v5, v37, v40
	v_fma_f32 v41, -v6, v38, v41
	v_fma_f32 v42, -v7, v39, v42
	ds_read_b128 v[112:115], v129 offset:58912
	ds_read_b128 v[108:111], v129 offset:58928
	ds_read_b128 v[104:107], v129 offset:58944
	ds_read_b128 v[100:103], v129 offset:58960
	ds_read_b128 v[36:39], v129 offset:58976
	s_waitcnt lgkmcnt(4)
	v_fma_f32 v35, -v8, v112, v35
	v_fma_f32 v40, -v9, v113, v40
	v_fma_f32 v41, -v10, v114, v41
	v_fma_f32 v42, -v11, v115, v42
	s_waitcnt lgkmcnt(3)
	v_fma_f32 v35, -v12, v108, v35
	v_fma_f32 v40, -v13, v109, v40
	v_fma_f32 v41, -v14, v110, v41
	v_fma_f32 v42, -v15, v111, v42
	s_waitcnt lgkmcnt(2)
	v_fma_f32 v35, -v16, v104, v35
	v_fma_f32 v40, -v17, v105, v40
	v_fma_f32 v41, -v18, v106, v41
	v_fma_f32 v42, -v19, v107, v42
	s_waitcnt lgkmcnt(1)
	v_fma_f32 v35, -v20, v100, v35
	v_fma_f32 v40, -v21, v101, v40
	v_fma_f32 v41, -v22, v102, v41
	v_fma_f32 v42, -v23, v103, v42
	s_waitcnt lgkmcnt(0)
	v_fma_f32 v35, -v24, v36, v35
	v_fma_f32 v40, -v25, v37, v40
	v_fma_f32 v41, -v26, v38, v41
	v_fma_f32 v42, -v27, v39, v42
	ds_read_b128 v[36:39], v129 offset:58992
	s_waitcnt lgkmcnt(0)
	v_fma_f32 v35, -v28, v36, v35
	v_fma_f32 v40, -v29, v37, v40
	v_fma_f32 v41, -v30, v38, v41
	ds_read_b96 v[36:38], v129 offset:59008
	v_fma_f32 v39, -v31, v39, v42
	s_waitcnt lgkmcnt(0)
	v_fma_f32 v35, -v32, v36, v35
	v_fma_f32 v36, -v33, v37, v40
	v_fma_f32 v37, -v34, v38, v41
	v_add_f32_e32 v35, v35, v36
	v_add_f32_e32 v36, v39, v37
	v_add_f32_e32 v35, v35, v36
	v_mov_b32_e32 v36, 0x10490
	v_mov_b32_e32 v40, 0x10690
	ds_read_b128 v[36:39], v36
	ds_read_b128 v[40:43], v40
	s_waitcnt lgkmcnt(0)
	v_cndmask_b32_e64 v36, v40, v36, s[44:45]
	v_mul_f32_e32 v40, v0, v44
	v_fma_f32 v36, v49, v36, -v40
	v_fma_f32 v40, -v1, v45, 0
	v_fma_f32 v49, -v3, v47, 0
	ds_read_b128 v[44:47], v129 offset:59152
	v_cndmask_b32_e64 v37, v41, v37, s[44:45]
	v_cndmask_b32_e64 v38, v42, v38, s[44:45]
	v_cndmask_b32_e64 v39, v43, v39, s[44:45]
	s_waitcnt lgkmcnt(0)
	v_fma_f32 v36, -v4, v44, v36
	v_fma_f32 v40, -v5, v45, v40
	v_fma_f32 v48, -v6, v46, v48
	v_fma_f32 v49, -v7, v47, v49
	ds_read_b128 v[116:119], v129 offset:59168
	ds_read_b128 v[112:115], v129 offset:59184
	ds_read_b128 v[108:111], v129 offset:59200
	ds_read_b128 v[104:107], v129 offset:59216
	ds_read_b128 v[100:103], v129 offset:59232
	ds_read_b128 v[44:47], v129 offset:59248
	s_waitcnt lgkmcnt(5)
	v_fma_f32 v36, -v8, v116, v36
	v_fma_f32 v40, -v9, v117, v40
	v_fma_f32 v48, -v10, v118, v48
	v_fma_f32 v49, -v11, v119, v49
	s_waitcnt lgkmcnt(4)
	v_fma_f32 v36, -v12, v112, v36
	v_fma_f32 v40, -v13, v113, v40
	v_fma_f32 v48, -v14, v114, v48
	v_fma_f32 v49, -v15, v115, v49
	s_waitcnt lgkmcnt(3)
	v_fma_f32 v36, -v16, v108, v36
	v_fma_f32 v40, -v17, v109, v40
	v_fma_f32 v48, -v18, v110, v48
	v_fma_f32 v49, -v19, v111, v49
	s_waitcnt lgkmcnt(2)
	v_fma_f32 v36, -v20, v104, v36
	v_fma_f32 v40, -v21, v105, v40
	v_fma_f32 v48, -v22, v106, v48
	v_fma_f32 v49, -v23, v107, v49
	s_waitcnt lgkmcnt(1)
	v_fma_f32 v36, -v24, v100, v36
	v_fma_f32 v40, -v25, v101, v40
	v_fma_f32 v48, -v26, v102, v48
	v_fma_f32 v49, -v27, v103, v49
	s_waitcnt lgkmcnt(0)
	v_fma_f32 v36, -v28, v44, v36
	v_fma_f32 v40, -v29, v45, v40
	v_fma_f32 v48, -v30, v46, v48
	v_fma_f32 v49, -v31, v47, v49
	ds_read_b128 v[44:47], v129 offset:59264
	s_waitcnt lgkmcnt(0)
	v_fma_f32 v36, -v32, v44, v36
	v_fma_f32 v40, -v33, v45, v40
	v_fma_f32 v44, -v34, v46, v48
	v_fma_f32 v45, -v35, v47, v49
	v_add_f32_e32 v36, v36, v40
	v_add_f32_e32 v40, v44, v45
	v_add_f32_e32 v36, v36, v40
	v_add_u32_e32 v40, 0x2400, v69
	ds_read_b128 v[44:47], v129 offset:59392
	ds_read2_b32 v[48:49], v40 offset0:101 offset1:166
	s_waitcnt lgkmcnt(1)
	v_mul_f32_e32 v40, v0, v44
	s_waitcnt lgkmcnt(0)
	v_fma_f32 v37, v48, v37, -v40
	v_fma_f32 v40, -v1, v45, 0
	v_fma_f32 v41, -v2, v46, 0
	v_fma_f32 v48, -v3, v47, 0
	ds_read_b128 v[120:123], v129 offset:59408
	ds_read_b128 v[116:119], v129 offset:59424
	ds_read_b128 v[112:115], v129 offset:59440
	ds_read_b128 v[108:111], v129 offset:59456
	ds_read_b128 v[104:107], v129 offset:59472
	ds_read_b128 v[100:103], v129 offset:59488
	ds_read_b128 v[44:47], v129 offset:59504
	s_waitcnt lgkmcnt(6)
	v_fma_f32 v37, -v4, v120, v37
	v_fma_f32 v40, -v5, v121, v40
	v_fma_f32 v41, -v6, v122, v41
	v_fma_f32 v48, -v7, v123, v48
	s_waitcnt lgkmcnt(5)
	v_fma_f32 v37, -v8, v116, v37
	v_fma_f32 v40, -v9, v117, v40
	v_fma_f32 v41, -v10, v118, v41
	v_fma_f32 v48, -v11, v119, v48
	s_waitcnt lgkmcnt(4)
	v_fma_f32 v37, -v12, v112, v37
	v_fma_f32 v40, -v13, v113, v40
	v_fma_f32 v41, -v14, v114, v41
	v_fma_f32 v48, -v15, v115, v48
	s_waitcnt lgkmcnt(3)
	v_fma_f32 v37, -v16, v108, v37
	v_fma_f32 v40, -v17, v109, v40
	v_fma_f32 v41, -v18, v110, v41
	v_fma_f32 v48, -v19, v111, v48
	s_waitcnt lgkmcnt(2)
	v_fma_f32 v37, -v20, v104, v37
	v_fma_f32 v40, -v21, v105, v40
	v_fma_f32 v41, -v22, v106, v41
	v_fma_f32 v48, -v23, v107, v48
	s_waitcnt lgkmcnt(1)
	v_fma_f32 v37, -v24, v100, v37
	v_fma_f32 v40, -v25, v101, v40
	v_fma_f32 v41, -v26, v102, v41
	v_fma_f32 v48, -v27, v103, v48
	s_waitcnt lgkmcnt(0)
	v_fma_f32 v37, -v28, v44, v37
	v_fma_f32 v40, -v29, v45, v40
	v_fma_f32 v41, -v30, v46, v41
	v_fma_f32 v48, -v31, v47, v48
	ds_read_b128 v[44:47], v129 offset:59520
	s_waitcnt lgkmcnt(0)
	v_fma_f32 v40, -v33, v45, v40
	ds_read_b32 v45, v129 offset:59536
	v_fma_f32 v37, -v32, v44, v37
	v_fma_f32 v41, -v34, v46, v41
	v_fma_f32 v44, -v35, v47, v48
	s_waitcnt lgkmcnt(0)
	v_fma_f32 v37, -v36, v45, v37
	v_add_f32_e32 v37, v40, v37
	v_add_f32_e32 v40, v41, v44
	ds_read_b128 v[44:47], v129 offset:59648
	v_add_f32_e32 v37, v40, v37
	s_waitcnt lgkmcnt(0)
	v_mul_f32_e32 v40, v0, v44
	v_fma_f32 v38, v49, v38, -v40
	v_fma_f32 v40, -v1, v45, 0
	v_fma_f32 v41, -v2, v46, 0
	v_fma_f32 v42, -v3, v47, 0
	ds_read_b128 v[44:47], v129 offset:59664
	ds_read_b128 v[48:51], v129 offset:60160
	s_waitcnt lgkmcnt(1)
	v_fma_f32 v38, -v4, v44, v38
	v_fma_f32 v40, -v5, v45, v40
	v_fma_f32 v41, -v6, v46, v41
	v_fma_f32 v42, -v7, v47, v42
	ds_read_b128 v[116:119], v129 offset:59680
	ds_read_b128 v[112:115], v129 offset:59696
	ds_read_b128 v[108:111], v129 offset:59712
	ds_read_b128 v[104:107], v129 offset:59728
	ds_read_b128 v[100:103], v129 offset:59744
	ds_read_b128 v[44:47], v129 offset:59760
	s_waitcnt lgkmcnt(5)
	v_fma_f32 v38, -v8, v116, v38
	v_fma_f32 v40, -v9, v117, v40
	v_fma_f32 v41, -v10, v118, v41
	v_fma_f32 v42, -v11, v119, v42
	s_waitcnt lgkmcnt(4)
	v_fma_f32 v38, -v12, v112, v38
	v_fma_f32 v40, -v13, v113, v40
	v_fma_f32 v41, -v14, v114, v41
	v_fma_f32 v42, -v15, v115, v42
	s_waitcnt lgkmcnt(3)
	v_fma_f32 v38, -v16, v108, v38
	v_fma_f32 v40, -v17, v109, v40
	v_fma_f32 v41, -v18, v110, v41
	v_fma_f32 v42, -v19, v111, v42
	s_waitcnt lgkmcnt(2)
	v_fma_f32 v38, -v20, v104, v38
	v_fma_f32 v40, -v21, v105, v40
	v_fma_f32 v41, -v22, v106, v41
	v_fma_f32 v42, -v23, v107, v42
	s_waitcnt lgkmcnt(1)
	v_fma_f32 v38, -v24, v100, v38
	v_fma_f32 v40, -v25, v101, v40
	v_fma_f32 v41, -v26, v102, v41
	v_fma_f32 v42, -v27, v103, v42
	s_waitcnt lgkmcnt(0)
	v_fma_f32 v38, -v28, v44, v38
	v_fma_f32 v40, -v29, v45, v40
	v_fma_f32 v41, -v30, v46, v41
	v_fma_f32 v42, -v31, v47, v42
	ds_read_b128 v[44:47], v129 offset:59776
	s_waitcnt lgkmcnt(0)
	v_fma_f32 v38, -v32, v44, v38
	v_fma_f32 v44, -v33, v45, v40
	v_fma_f32 v45, -v34, v46, v41
	ds_read_b64 v[40:41], v129 offset:59792
	v_fma_f32 v42, -v35, v47, v42
	s_waitcnt lgkmcnt(0)
	v_fma_f32 v38, -v36, v40, v38
	v_fma_f32 v40, -v37, v41, v44
	v_add_f32_e32 v38, v38, v40
	v_add_f32_e32 v40, v45, v42
	v_add_f32_e32 v38, v40, v38
	v_add_u32_e32 v40, 0x2600, v69
	ds_read2_b32 v[52:53], v40 offset0:103 offset1:168
	ds_read_b128 v[40:43], v129 offset:59904
	s_waitcnt lgkmcnt(0)
	v_mul_f32_e32 v40, v0, v40
	v_fma_f32 v39, v52, v39, -v40
	v_fma_f32 v44, -v1, v41, 0
	v_fma_f32 v45, -v2, v42, 0
	v_fma_f32 v46, -v3, v43, 0
	ds_read_b128 v[40:43], v129 offset:59920
	v_fma_f32 v52, -v2, v50, 0
	s_waitcnt lgkmcnt(0)
	v_fma_f32 v39, -v4, v40, v39
	v_fma_f32 v44, -v5, v41, v44
	v_fma_f32 v45, -v6, v42, v45
	v_fma_f32 v46, -v7, v43, v46
	ds_read_b128 v[116:119], v129 offset:59936
	ds_read_b128 v[112:115], v129 offset:59952
	ds_read_b128 v[108:111], v129 offset:59968
	ds_read_b128 v[104:107], v129 offset:59984
	ds_read_b128 v[100:103], v129 offset:60000
	ds_read_b128 v[40:43], v129 offset:60016
	s_waitcnt lgkmcnt(5)
	v_fma_f32 v39, -v8, v116, v39
	v_fma_f32 v44, -v9, v117, v44
	v_fma_f32 v45, -v10, v118, v45
	v_fma_f32 v46, -v11, v119, v46
	s_waitcnt lgkmcnt(4)
	v_fma_f32 v39, -v12, v112, v39
	v_fma_f32 v44, -v13, v113, v44
	v_fma_f32 v45, -v14, v114, v45
	v_fma_f32 v46, -v15, v115, v46
	s_waitcnt lgkmcnt(3)
	v_fma_f32 v39, -v16, v108, v39
	v_fma_f32 v44, -v17, v109, v44
	v_fma_f32 v45, -v18, v110, v45
	v_fma_f32 v46, -v19, v111, v46
	s_waitcnt lgkmcnt(2)
	v_fma_f32 v39, -v20, v104, v39
	v_fma_f32 v44, -v21, v105, v44
	v_fma_f32 v45, -v22, v106, v45
	v_fma_f32 v46, -v23, v107, v46
	s_waitcnt lgkmcnt(1)
	v_fma_f32 v39, -v24, v100, v39
	v_fma_f32 v44, -v25, v101, v44
	v_fma_f32 v45, -v26, v102, v45
	v_fma_f32 v46, -v27, v103, v46
	s_waitcnt lgkmcnt(0)
	v_fma_f32 v39, -v28, v40, v39
	v_fma_f32 v44, -v29, v41, v44
	v_fma_f32 v45, -v30, v42, v45
	v_fma_f32 v46, -v31, v43, v46
	ds_read_b128 v[40:43], v129 offset:60032
	s_waitcnt lgkmcnt(0)
	v_fma_f32 v39, -v32, v40, v39
	v_fma_f32 v44, -v33, v41, v44
	v_fma_f32 v45, -v34, v42, v45
	ds_read_b96 v[40:42], v129 offset:60048
	v_fma_f32 v43, -v35, v43, v46
	s_waitcnt lgkmcnt(0)
	v_fma_f32 v39, -v36, v40, v39
	v_fma_f32 v40, -v37, v41, v44
	v_fma_f32 v41, -v38, v42, v45
	v_add_f32_e32 v39, v39, v40
	v_add_f32_e32 v40, v43, v41
	v_add_f32_e32 v39, v39, v40
	v_mov_b32_e32 v40, 0x104a0
	v_mov_b32_e32 v44, 0x106a0
	ds_read_b128 v[40:43], v40
	ds_read_b128 v[44:47], v44
	s_waitcnt lgkmcnt(0)
	v_cndmask_b32_e64 v40, v44, v40, s[44:45]
	v_mul_f32_e32 v44, v0, v48
	v_fma_f32 v40, v53, v40, -v44
	v_fma_f32 v44, -v1, v49, 0
	v_fma_f32 v53, -v3, v51, 0
	ds_read_b128 v[48:51], v129 offset:60176
	v_cndmask_b32_e64 v41, v45, v41, s[44:45]
	v_cndmask_b32_e64 v42, v46, v42, s[44:45]
	v_cndmask_b32_e64 v43, v47, v43, s[44:45]
	s_waitcnt lgkmcnt(0)
	v_fma_f32 v40, -v4, v48, v40
	v_fma_f32 v44, -v5, v49, v44
	v_fma_f32 v52, -v6, v50, v52
	v_fma_f32 v53, -v7, v51, v53
	ds_read_b128 v[120:123], v129 offset:60192
	ds_read_b128 v[116:119], v129 offset:60208
	ds_read_b128 v[112:115], v129 offset:60224
	ds_read_b128 v[108:111], v129 offset:60240
	ds_read_b128 v[104:107], v129 offset:60256
	ds_read_b128 v[100:103], v129 offset:60272
	ds_read_b128 v[48:51], v129 offset:60288
	s_waitcnt lgkmcnt(6)
	v_fma_f32 v40, -v8, v120, v40
	v_fma_f32 v44, -v9, v121, v44
	v_fma_f32 v52, -v10, v122, v52
	v_fma_f32 v53, -v11, v123, v53
	s_waitcnt lgkmcnt(5)
	v_fma_f32 v40, -v12, v116, v40
	v_fma_f32 v44, -v13, v117, v44
	v_fma_f32 v52, -v14, v118, v52
	v_fma_f32 v53, -v15, v119, v53
	s_waitcnt lgkmcnt(4)
	v_fma_f32 v40, -v16, v112, v40
	v_fma_f32 v44, -v17, v113, v44
	v_fma_f32 v52, -v18, v114, v52
	v_fma_f32 v53, -v19, v115, v53
	s_waitcnt lgkmcnt(3)
	v_fma_f32 v40, -v20, v108, v40
	v_fma_f32 v44, -v21, v109, v44
	v_fma_f32 v52, -v22, v110, v52
	v_fma_f32 v53, -v23, v111, v53
	s_waitcnt lgkmcnt(2)
	v_fma_f32 v40, -v24, v104, v40
	v_fma_f32 v44, -v25, v105, v44
	v_fma_f32 v52, -v26, v106, v52
	v_fma_f32 v53, -v27, v107, v53
	s_waitcnt lgkmcnt(1)
	v_fma_f32 v40, -v28, v100, v40
	v_fma_f32 v44, -v29, v101, v44
	v_fma_f32 v52, -v30, v102, v52
	v_fma_f32 v53, -v31, v103, v53
	s_waitcnt lgkmcnt(0)
	v_fma_f32 v40, -v32, v48, v40
	v_fma_f32 v44, -v33, v49, v44
	v_fma_f32 v52, -v34, v50, v52
	v_fma_f32 v53, -v35, v51, v53
	ds_read_b128 v[48:51], v129 offset:60304
	s_waitcnt lgkmcnt(0)
	v_fma_f32 v40, -v36, v48, v40
	v_fma_f32 v44, -v37, v49, v44
	v_fma_f32 v48, -v38, v50, v52
	v_fma_f32 v49, -v39, v51, v53
	v_add_f32_e32 v40, v40, v44
	v_add_f32_e32 v44, v48, v49
	v_add_f32_e32 v40, v40, v44
	v_add_u32_e32 v44, 0x2800, v69
	ds_read_b128 v[48:51], v129 offset:60416
	ds_read2_b32 v[52:53], v44 offset0:105 offset1:170
	s_waitcnt lgkmcnt(1)
	v_mul_f32_e32 v44, v0, v48
	s_waitcnt lgkmcnt(0)
	v_fma_f32 v41, v52, v41, -v44
	v_fma_f32 v44, -v1, v49, 0
	v_fma_f32 v45, -v2, v50, 0
	v_fma_f32 v52, -v3, v51, 0
	ds_read_b128 v[124:127], v129 offset:60432
	ds_read_b128 v[120:123], v129 offset:60448
	ds_read_b128 v[116:119], v129 offset:60464
	ds_read_b128 v[112:115], v129 offset:60480
	ds_read_b128 v[108:111], v129 offset:60496
	ds_read_b128 v[104:107], v129 offset:60512
	ds_read_b128 v[100:103], v129 offset:60528
	ds_read_b128 v[48:51], v129 offset:60544
	s_waitcnt lgkmcnt(7)
	v_fma_f32 v41, -v4, v124, v41
	v_fma_f32 v44, -v5, v125, v44
	v_fma_f32 v45, -v6, v126, v45
	v_fma_f32 v52, -v7, v127, v52
	s_waitcnt lgkmcnt(6)
	v_fma_f32 v41, -v8, v120, v41
	v_fma_f32 v44, -v9, v121, v44
	v_fma_f32 v45, -v10, v122, v45
	v_fma_f32 v52, -v11, v123, v52
	s_waitcnt lgkmcnt(5)
	v_fma_f32 v41, -v12, v116, v41
	v_fma_f32 v44, -v13, v117, v44
	v_fma_f32 v45, -v14, v118, v45
	v_fma_f32 v52, -v15, v119, v52
	s_waitcnt lgkmcnt(4)
	v_fma_f32 v41, -v16, v112, v41
	v_fma_f32 v44, -v17, v113, v44
	v_fma_f32 v45, -v18, v114, v45
	v_fma_f32 v52, -v19, v115, v52
	s_waitcnt lgkmcnt(3)
	v_fma_f32 v41, -v20, v108, v41
	v_fma_f32 v44, -v21, v109, v44
	v_fma_f32 v45, -v22, v110, v45
	v_fma_f32 v52, -v23, v111, v52
	s_waitcnt lgkmcnt(2)
	v_fma_f32 v41, -v24, v104, v41
	v_fma_f32 v44, -v25, v105, v44
	v_fma_f32 v45, -v26, v106, v45
	v_fma_f32 v52, -v27, v107, v52
	s_waitcnt lgkmcnt(1)
	v_fma_f32 v41, -v28, v100, v41
	v_fma_f32 v44, -v29, v101, v44
	v_fma_f32 v45, -v30, v102, v45
	v_fma_f32 v52, -v31, v103, v52
	s_waitcnt lgkmcnt(0)
	v_fma_f32 v41, -v32, v48, v41
	v_fma_f32 v44, -v33, v49, v44
	v_fma_f32 v45, -v34, v50, v45
	v_fma_f32 v52, -v35, v51, v52
	ds_read_b128 v[48:51], v129 offset:60560
	s_waitcnt lgkmcnt(0)
	v_fma_f32 v44, -v37, v49, v44
	ds_read_b32 v49, v129 offset:60576
	v_fma_f32 v41, -v36, v48, v41
	v_fma_f32 v45, -v38, v50, v45
	v_fma_f32 v48, -v39, v51, v52
	s_waitcnt lgkmcnt(0)
	v_fma_f32 v41, -v40, v49, v41
	v_add_f32_e32 v41, v44, v41
	v_add_f32_e32 v44, v45, v48
	ds_read_b128 v[48:51], v129 offset:60672
	v_add_f32_e32 v41, v44, v41
	s_waitcnt lgkmcnt(0)
	v_mul_f32_e32 v44, v0, v48
	v_fma_f32 v42, v53, v42, -v44
	v_fma_f32 v44, -v1, v49, 0
	v_fma_f32 v45, -v2, v50, 0
	v_fma_f32 v46, -v3, v51, 0
	ds_read_b128 v[48:51], v129 offset:60688
	ds_read_b128 v[52:55], v129 offset:61184
	s_waitcnt lgkmcnt(1)
	v_fma_f32 v42, -v4, v48, v42
	v_fma_f32 v44, -v5, v49, v44
	v_fma_f32 v45, -v6, v50, v45
	v_fma_f32 v46, -v7, v51, v46
	ds_read_b128 v[120:123], v129 offset:60704
	ds_read_b128 v[116:119], v129 offset:60720
	ds_read_b128 v[112:115], v129 offset:60736
	ds_read_b128 v[108:111], v129 offset:60752
	ds_read_b128 v[104:107], v129 offset:60768
	ds_read_b128 v[100:103], v129 offset:60784
	ds_read_b128 v[48:51], v129 offset:60800
	s_waitcnt lgkmcnt(6)
	v_fma_f32 v42, -v8, v120, v42
	v_fma_f32 v44, -v9, v121, v44
	v_fma_f32 v45, -v10, v122, v45
	v_fma_f32 v46, -v11, v123, v46
	s_waitcnt lgkmcnt(5)
	v_fma_f32 v42, -v12, v116, v42
	v_fma_f32 v44, -v13, v117, v44
	v_fma_f32 v45, -v14, v118, v45
	v_fma_f32 v46, -v15, v119, v46
	s_waitcnt lgkmcnt(4)
	v_fma_f32 v42, -v16, v112, v42
	v_fma_f32 v44, -v17, v113, v44
	v_fma_f32 v45, -v18, v114, v45
	v_fma_f32 v46, -v19, v115, v46
	s_waitcnt lgkmcnt(3)
	v_fma_f32 v42, -v20, v108, v42
	v_fma_f32 v44, -v21, v109, v44
	v_fma_f32 v45, -v22, v110, v45
	v_fma_f32 v46, -v23, v111, v46
	s_waitcnt lgkmcnt(2)
	v_fma_f32 v42, -v24, v104, v42
	v_fma_f32 v44, -v25, v105, v44
	v_fma_f32 v45, -v26, v106, v45
	v_fma_f32 v46, -v27, v107, v46
	s_waitcnt lgkmcnt(1)
	v_fma_f32 v42, -v28, v100, v42
	v_fma_f32 v44, -v29, v101, v44
	v_fma_f32 v45, -v30, v102, v45
	v_fma_f32 v46, -v31, v103, v46
	s_waitcnt lgkmcnt(0)
	v_fma_f32 v42, -v32, v48, v42
	v_fma_f32 v44, -v33, v49, v44
	v_fma_f32 v45, -v34, v50, v45
	v_fma_f32 v46, -v35, v51, v46
	ds_read_b128 v[48:51], v129 offset:60816
	s_waitcnt lgkmcnt(0)
	v_fma_f32 v42, -v36, v48, v42
	v_fma_f32 v48, -v37, v49, v44
	v_fma_f32 v49, -v38, v50, v45
	ds_read_b64 v[44:45], v129 offset:60832
	v_fma_f32 v46, -v39, v51, v46
	s_waitcnt lgkmcnt(0)
	v_fma_f32 v42, -v40, v44, v42
	v_fma_f32 v44, -v41, v45, v48
	v_add_f32_e32 v42, v42, v44
	v_add_f32_e32 v44, v49, v46
	v_add_f32_e32 v42, v44, v42
	v_add_u32_e32 v44, 0x2a00, v69
	ds_read2_b32 v[56:57], v44 offset0:107 offset1:172
	ds_read_b128 v[44:47], v129 offset:60928
	s_waitcnt lgkmcnt(0)
	v_mul_f32_e32 v44, v0, v44
	v_fma_f32 v43, v56, v43, -v44
	v_fma_f32 v48, -v1, v45, 0
	v_fma_f32 v49, -v2, v46, 0
	v_fma_f32 v50, -v3, v47, 0
	ds_read_b128 v[44:47], v129 offset:60944
	v_fma_f32 v56, -v2, v54, 0
	s_waitcnt lgkmcnt(0)
	v_fma_f32 v43, -v4, v44, v43
	v_fma_f32 v48, -v5, v45, v48
	v_fma_f32 v49, -v6, v46, v49
	v_fma_f32 v50, -v7, v47, v50
	ds_read_b128 v[120:123], v129 offset:60960
	ds_read_b128 v[116:119], v129 offset:60976
	ds_read_b128 v[112:115], v129 offset:60992
	ds_read_b128 v[108:111], v129 offset:61008
	ds_read_b128 v[104:107], v129 offset:61024
	ds_read_b128 v[100:103], v129 offset:61040
	ds_read_b128 v[44:47], v129 offset:61056
	s_waitcnt lgkmcnt(6)
	v_fma_f32 v43, -v8, v120, v43
	v_fma_f32 v48, -v9, v121, v48
	v_fma_f32 v49, -v10, v122, v49
	v_fma_f32 v50, -v11, v123, v50
	s_waitcnt lgkmcnt(5)
	v_fma_f32 v43, -v12, v116, v43
	v_fma_f32 v48, -v13, v117, v48
	v_fma_f32 v49, -v14, v118, v49
	v_fma_f32 v50, -v15, v119, v50
	s_waitcnt lgkmcnt(4)
	v_fma_f32 v43, -v16, v112, v43
	v_fma_f32 v48, -v17, v113, v48
	v_fma_f32 v49, -v18, v114, v49
	v_fma_f32 v50, -v19, v115, v50
	s_waitcnt lgkmcnt(3)
	v_fma_f32 v43, -v20, v108, v43
	v_fma_f32 v48, -v21, v109, v48
	v_fma_f32 v49, -v22, v110, v49
	v_fma_f32 v50, -v23, v111, v50
	s_waitcnt lgkmcnt(2)
	v_fma_f32 v43, -v24, v104, v43
	v_fma_f32 v48, -v25, v105, v48
	v_fma_f32 v49, -v26, v106, v49
	v_fma_f32 v50, -v27, v107, v50
	s_waitcnt lgkmcnt(1)
	v_fma_f32 v43, -v28, v100, v43
	v_fma_f32 v48, -v29, v101, v48
	v_fma_f32 v49, -v30, v102, v49
	v_fma_f32 v50, -v31, v103, v50
	s_waitcnt lgkmcnt(0)
	v_fma_f32 v43, -v32, v44, v43
	v_fma_f32 v48, -v33, v45, v48
	v_fma_f32 v49, -v34, v46, v49
	v_fma_f32 v50, -v35, v47, v50
	ds_read_b128 v[44:47], v129 offset:61072
	s_waitcnt lgkmcnt(0)
	v_fma_f32 v43, -v36, v44, v43
	v_fma_f32 v48, -v37, v45, v48
	v_fma_f32 v49, -v38, v46, v49
	ds_read_b96 v[44:46], v129 offset:61088
	v_fma_f32 v47, -v39, v47, v50
	s_waitcnt lgkmcnt(0)
	v_fma_f32 v43, -v40, v44, v43
	v_fma_f32 v44, -v41, v45, v48
	v_fma_f32 v45, -v42, v46, v49
	v_add_f32_e32 v43, v43, v44
	v_add_f32_e32 v44, v47, v45
	v_add_f32_e32 v43, v43, v44
	v_mov_b32_e32 v44, 0x104b0
	v_mov_b32_e32 v48, 0x106b0
	ds_read_b128 v[44:47], v44
	ds_read_b128 v[48:51], v48
	s_waitcnt lgkmcnt(0)
	v_cndmask_b32_e64 v44, v48, v44, s[44:45]
	v_mul_f32_e32 v48, v0, v52
	v_fma_f32 v44, v57, v44, -v48
	v_fma_f32 v48, -v1, v53, 0
	v_fma_f32 v57, -v3, v55, 0
	ds_read_b128 v[52:55], v129 offset:61200
	v_cndmask_b32_e64 v45, v49, v45, s[44:45]
	v_cndmask_b32_e64 v46, v50, v46, s[44:45]
	v_cndmask_b32_e64 v47, v51, v47, s[44:45]
	s_waitcnt lgkmcnt(0)
	v_fma_f32 v44, -v4, v52, v44
	v_fma_f32 v48, -v5, v53, v48
	v_fma_f32 v56, -v6, v54, v56
	v_fma_f32 v57, -v7, v55, v57
	ds_read_b128 v[124:127], v129 offset:61216
	ds_read_b128 v[120:123], v129 offset:61232
	ds_read_b128 v[116:119], v129 offset:61248
	ds_read_b128 v[112:115], v129 offset:61264
	ds_read_b128 v[108:111], v129 offset:61280
	ds_read_b128 v[104:107], v129 offset:61296
	ds_read_b128 v[100:103], v129 offset:61312
	ds_read_b128 v[52:55], v129 offset:61328
	s_waitcnt lgkmcnt(7)
	v_fma_f32 v44, -v8, v124, v44
	v_fma_f32 v48, -v9, v125, v48
	v_fma_f32 v56, -v10, v126, v56
	v_fma_f32 v57, -v11, v127, v57
	s_waitcnt lgkmcnt(6)
	v_fma_f32 v44, -v12, v120, v44
	v_fma_f32 v48, -v13, v121, v48
	v_fma_f32 v56, -v14, v122, v56
	v_fma_f32 v57, -v15, v123, v57
	s_waitcnt lgkmcnt(5)
	v_fma_f32 v44, -v16, v116, v44
	v_fma_f32 v48, -v17, v117, v48
	v_fma_f32 v56, -v18, v118, v56
	v_fma_f32 v57, -v19, v119, v57
	s_waitcnt lgkmcnt(4)
	v_fma_f32 v44, -v20, v112, v44
	v_fma_f32 v48, -v21, v113, v48
	v_fma_f32 v56, -v22, v114, v56
	v_fma_f32 v57, -v23, v115, v57
	s_waitcnt lgkmcnt(3)
	v_fma_f32 v44, -v24, v108, v44
	v_fma_f32 v48, -v25, v109, v48
	v_fma_f32 v56, -v26, v110, v56
	v_fma_f32 v57, -v27, v111, v57
	s_waitcnt lgkmcnt(2)
	v_fma_f32 v44, -v28, v104, v44
	v_fma_f32 v48, -v29, v105, v48
	v_fma_f32 v56, -v30, v106, v56
	v_fma_f32 v57, -v31, v107, v57
	s_waitcnt lgkmcnt(1)
	v_fma_f32 v44, -v32, v100, v44
	v_fma_f32 v48, -v33, v101, v48
	v_fma_f32 v56, -v34, v102, v56
	v_fma_f32 v57, -v35, v103, v57
	s_waitcnt lgkmcnt(0)
	v_fma_f32 v44, -v36, v52, v44
	v_fma_f32 v48, -v37, v53, v48
	v_fma_f32 v56, -v38, v54, v56
	v_fma_f32 v57, -v39, v55, v57
	ds_read_b128 v[52:55], v129 offset:61344
	s_waitcnt lgkmcnt(0)
	v_fma_f32 v44, -v40, v52, v44
	v_fma_f32 v48, -v41, v53, v48
	v_fma_f32 v52, -v42, v54, v56
	v_fma_f32 v53, -v43, v55, v57
	v_add_f32_e32 v44, v44, v48
	v_add_f32_e32 v48, v52, v53
	v_add_f32_e32 v44, v44, v48
	v_add_u32_e32 v48, 0x2c00, v69
	ds_read_b128 v[52:55], v129 offset:61440
	ds_read2_b32 v[56:57], v48 offset0:109 offset1:174
	s_waitcnt lgkmcnt(1)
	v_mul_f32_e32 v48, v0, v52
	s_waitcnt lgkmcnt(0)
	v_fma_f32 v45, v56, v45, -v48
	v_fma_f32 v48, -v1, v53, 0
	v_fma_f32 v49, -v2, v54, 0
	v_fma_f32 v56, -v3, v55, 0
	ds_read_b128 v[52:55], v129 offset:61456
	ds_read_b128 v[124:127], v129 offset:61472
	ds_read_b128 v[120:123], v129 offset:61488
	ds_read_b128 v[116:119], v129 offset:61504
	ds_read_b128 v[112:115], v129 offset:61520
	ds_read_b128 v[108:111], v129 offset:61536
	ds_read_b128 v[104:107], v129 offset:61552
	ds_read_b128 v[100:103], v129 offset:61568
	s_waitcnt lgkmcnt(7)
	v_fma_f32 v45, -v4, v52, v45
	v_fma_f32 v48, -v5, v53, v48
	v_fma_f32 v49, -v6, v54, v49
	v_fma_f32 v56, -v7, v55, v56
	ds_read_b128 v[52:55], v129 offset:61584
	s_waitcnt lgkmcnt(7)
	v_fma_f32 v45, -v8, v124, v45
	v_fma_f32 v48, -v9, v125, v48
	v_fma_f32 v49, -v10, v126, v49
	v_fma_f32 v56, -v11, v127, v56
	s_waitcnt lgkmcnt(6)
	v_fma_f32 v45, -v12, v120, v45
	v_fma_f32 v48, -v13, v121, v48
	v_fma_f32 v49, -v14, v122, v49
	v_fma_f32 v56, -v15, v123, v56
	s_waitcnt lgkmcnt(5)
	v_fma_f32 v45, -v16, v116, v45
	v_fma_f32 v48, -v17, v117, v48
	v_fma_f32 v49, -v18, v118, v49
	v_fma_f32 v56, -v19, v119, v56
	s_waitcnt lgkmcnt(4)
	v_fma_f32 v45, -v20, v112, v45
	v_fma_f32 v48, -v21, v113, v48
	v_fma_f32 v49, -v22, v114, v49
	v_fma_f32 v56, -v23, v115, v56
	s_waitcnt lgkmcnt(3)
	v_fma_f32 v45, -v24, v108, v45
	v_fma_f32 v48, -v25, v109, v48
	v_fma_f32 v49, -v26, v110, v49
	v_fma_f32 v56, -v27, v111, v56
	s_waitcnt lgkmcnt(2)
	v_fma_f32 v45, -v28, v104, v45
	v_fma_f32 v48, -v29, v105, v48
	v_fma_f32 v49, -v30, v106, v49
	v_fma_f32 v56, -v31, v107, v56
	s_waitcnt lgkmcnt(1)
	v_fma_f32 v45, -v32, v100, v45
	v_fma_f32 v48, -v33, v101, v48
	v_fma_f32 v49, -v34, v102, v49
	v_fma_f32 v56, -v35, v103, v56
	s_waitcnt lgkmcnt(0)
	v_fma_f32 v45, -v36, v52, v45
	v_fma_f32 v48, -v37, v53, v48
	v_fma_f32 v49, -v38, v54, v49
	v_fma_f32 v56, -v39, v55, v56
	ds_read_b128 v[52:55], v129 offset:61600
	s_waitcnt lgkmcnt(0)
	v_fma_f32 v48, -v41, v53, v48
	ds_read_b32 v53, v129 offset:61616
	v_fma_f32 v45, -v40, v52, v45
	v_fma_f32 v49, -v42, v54, v49
	v_fma_f32 v52, -v43, v55, v56
	s_waitcnt lgkmcnt(0)
	v_fma_f32 v45, -v44, v53, v45
	v_add_f32_e32 v45, v48, v45
	v_add_f32_e32 v48, v49, v52
	ds_read_b128 v[52:55], v129 offset:61696
	v_add_f32_e32 v45, v48, v45
	s_waitcnt lgkmcnt(0)
	v_mul_f32_e32 v48, v0, v52
	v_fma_f32 v46, v57, v46, -v48
	v_fma_f32 v48, -v1, v53, 0
	v_fma_f32 v49, -v2, v54, 0
	v_fma_f32 v50, -v3, v55, 0
	ds_read_b128 v[52:55], v129 offset:61712
	ds_read_b128 v[56:59], v129 offset:62208
	s_waitcnt lgkmcnt(1)
	v_fma_f32 v46, -v4, v52, v46
	v_fma_f32 v48, -v5, v53, v48
	v_fma_f32 v49, -v6, v54, v49
	v_fma_f32 v50, -v7, v55, v50
	ds_read_b128 v[124:127], v129 offset:61728
	ds_read_b128 v[120:123], v129 offset:61744
	ds_read_b128 v[116:119], v129 offset:61760
	ds_read_b128 v[112:115], v129 offset:61776
	ds_read_b128 v[108:111], v129 offset:61792
	ds_read_b128 v[104:107], v129 offset:61808
	ds_read_b128 v[100:103], v129 offset:61824
	ds_read_b128 v[52:55], v129 offset:61840
	s_waitcnt lgkmcnt(7)
	v_fma_f32 v46, -v8, v124, v46
	v_fma_f32 v48, -v9, v125, v48
	v_fma_f32 v49, -v10, v126, v49
	v_fma_f32 v50, -v11, v127, v50
	s_waitcnt lgkmcnt(6)
	v_fma_f32 v46, -v12, v120, v46
	v_fma_f32 v48, -v13, v121, v48
	v_fma_f32 v49, -v14, v122, v49
	v_fma_f32 v50, -v15, v123, v50
	s_waitcnt lgkmcnt(5)
	v_fma_f32 v46, -v16, v116, v46
	v_fma_f32 v48, -v17, v117, v48
	v_fma_f32 v49, -v18, v118, v49
	v_fma_f32 v50, -v19, v119, v50
	s_waitcnt lgkmcnt(4)
	v_fma_f32 v46, -v20, v112, v46
	v_fma_f32 v48, -v21, v113, v48
	v_fma_f32 v49, -v22, v114, v49
	v_fma_f32 v50, -v23, v115, v50
	s_waitcnt lgkmcnt(3)
	v_fma_f32 v46, -v24, v108, v46
	v_fma_f32 v48, -v25, v109, v48
	v_fma_f32 v49, -v26, v110, v49
	v_fma_f32 v50, -v27, v111, v50
	s_waitcnt lgkmcnt(2)
	v_fma_f32 v46, -v28, v104, v46
	v_fma_f32 v48, -v29, v105, v48
	v_fma_f32 v49, -v30, v106, v49
	v_fma_f32 v50, -v31, v107, v50
	s_waitcnt lgkmcnt(1)
	v_fma_f32 v46, -v32, v100, v46
	v_fma_f32 v48, -v33, v101, v48
	v_fma_f32 v49, -v34, v102, v49
	v_fma_f32 v50, -v35, v103, v50
	s_waitcnt lgkmcnt(0)
	v_fma_f32 v46, -v36, v52, v46
	v_fma_f32 v48, -v37, v53, v48
	v_fma_f32 v49, -v38, v54, v49
	v_fma_f32 v50, -v39, v55, v50
	ds_read_b128 v[52:55], v129 offset:61856
	s_waitcnt lgkmcnt(0)
	v_fma_f32 v46, -v40, v52, v46
	v_fma_f32 v52, -v41, v53, v48
	v_fma_f32 v53, -v42, v54, v49
	ds_read_b64 v[48:49], v129 offset:61872
	v_fma_f32 v50, -v43, v55, v50
	s_waitcnt lgkmcnt(0)
	v_fma_f32 v46, -v44, v48, v46
	v_fma_f32 v48, -v45, v49, v52
	v_add_f32_e32 v46, v46, v48
	v_add_f32_e32 v48, v53, v50
	v_add_f32_e32 v46, v48, v46
	v_add_u32_e32 v48, 0x2e00, v69
	ds_read2_b32 v[60:61], v48 offset0:111 offset1:176
	ds_read_b128 v[48:51], v129 offset:61952
	s_waitcnt lgkmcnt(0)
	v_mul_f32_e32 v48, v0, v48
	v_fma_f32 v47, v60, v47, -v48
	v_fma_f32 v52, -v1, v49, 0
	v_fma_f32 v53, -v2, v50, 0
	v_fma_f32 v54, -v3, v51, 0
	ds_read_b128 v[48:51], v129 offset:61968
	v_fma_f32 v60, -v2, v58, 0
	s_waitcnt lgkmcnt(0)
	v_fma_f32 v47, -v4, v48, v47
	v_fma_f32 v52, -v5, v49, v52
	v_fma_f32 v53, -v6, v50, v53
	v_fma_f32 v54, -v7, v51, v54
	ds_read_b128 v[124:127], v129 offset:61984
	ds_read_b128 v[120:123], v129 offset:62000
	ds_read_b128 v[116:119], v129 offset:62016
	ds_read_b128 v[112:115], v129 offset:62032
	ds_read_b128 v[108:111], v129 offset:62048
	ds_read_b128 v[104:107], v129 offset:62064
	ds_read_b128 v[100:103], v129 offset:62080
	ds_read_b128 v[48:51], v129 offset:62096
	s_waitcnt lgkmcnt(7)
	v_fma_f32 v47, -v8, v124, v47
	v_fma_f32 v52, -v9, v125, v52
	v_fma_f32 v53, -v10, v126, v53
	v_fma_f32 v54, -v11, v127, v54
	s_waitcnt lgkmcnt(6)
	v_fma_f32 v47, -v12, v120, v47
	v_fma_f32 v52, -v13, v121, v52
	v_fma_f32 v53, -v14, v122, v53
	v_fma_f32 v54, -v15, v123, v54
	s_waitcnt lgkmcnt(5)
	v_fma_f32 v47, -v16, v116, v47
	v_fma_f32 v52, -v17, v117, v52
	v_fma_f32 v53, -v18, v118, v53
	v_fma_f32 v54, -v19, v119, v54
	s_waitcnt lgkmcnt(4)
	v_fma_f32 v47, -v20, v112, v47
	v_fma_f32 v52, -v21, v113, v52
	v_fma_f32 v53, -v22, v114, v53
	v_fma_f32 v54, -v23, v115, v54
	s_waitcnt lgkmcnt(3)
	v_fma_f32 v47, -v24, v108, v47
	v_fma_f32 v52, -v25, v109, v52
	v_fma_f32 v53, -v26, v110, v53
	v_fma_f32 v54, -v27, v111, v54
	s_waitcnt lgkmcnt(2)
	v_fma_f32 v47, -v28, v104, v47
	v_fma_f32 v52, -v29, v105, v52
	v_fma_f32 v53, -v30, v106, v53
	v_fma_f32 v54, -v31, v107, v54
	s_waitcnt lgkmcnt(1)
	v_fma_f32 v47, -v32, v100, v47
	v_fma_f32 v52, -v33, v101, v52
	v_fma_f32 v53, -v34, v102, v53
	v_fma_f32 v54, -v35, v103, v54
	s_waitcnt lgkmcnt(0)
	v_fma_f32 v47, -v36, v48, v47
	v_fma_f32 v52, -v37, v49, v52
	v_fma_f32 v53, -v38, v50, v53
	v_fma_f32 v54, -v39, v51, v54
	ds_read_b128 v[48:51], v129 offset:62112
	s_waitcnt lgkmcnt(0)
	v_fma_f32 v47, -v40, v48, v47
	v_fma_f32 v52, -v41, v49, v52
	v_fma_f32 v53, -v42, v50, v53
	ds_read_b96 v[48:50], v129 offset:62128
	v_fma_f32 v51, -v43, v51, v54
	s_waitcnt lgkmcnt(0)
	v_fma_f32 v47, -v44, v48, v47
	v_fma_f32 v48, -v45, v49, v52
	v_fma_f32 v49, -v46, v50, v53
	v_add_f32_e32 v47, v47, v48
	v_add_f32_e32 v48, v51, v49
	v_add_f32_e32 v47, v47, v48
	v_mov_b32_e32 v48, 0x104c0
	v_mov_b32_e32 v52, 0x106c0
	ds_read_b128 v[48:51], v48
	ds_read_b128 v[52:55], v52
	s_waitcnt lgkmcnt(0)
	v_cndmask_b32_e64 v48, v52, v48, s[44:45]
	v_mul_f32_e32 v52, v0, v56
	v_fma_f32 v48, v61, v48, -v52
	v_fma_f32 v52, -v1, v57, 0
	v_fma_f32 v61, -v3, v59, 0
	ds_read_b128 v[56:59], v129 offset:62224
	v_cndmask_b32_e64 v49, v53, v49, s[44:45]
	v_cndmask_b32_e64 v50, v54, v50, s[44:45]
	v_cndmask_b32_e64 v51, v55, v51, s[44:45]
	s_waitcnt lgkmcnt(0)
	v_fma_f32 v48, -v4, v56, v48
	v_fma_f32 v52, -v5, v57, v52
	v_fma_f32 v60, -v6, v58, v60
	v_fma_f32 v61, -v7, v59, v61
	ds_read_b128 v[56:59], v129 offset:62240
	ds_read_b128 v[124:127], v129 offset:62256
	ds_read_b128 v[120:123], v129 offset:62272
	ds_read_b128 v[116:119], v129 offset:62288
	ds_read_b128 v[112:115], v129 offset:62304
	ds_read_b128 v[108:111], v129 offset:62320
	ds_read_b128 v[104:107], v129 offset:62336
	ds_read_b128 v[100:103], v129 offset:62352
	s_waitcnt lgkmcnt(7)
	v_fma_f32 v48, -v8, v56, v48
	v_fma_f32 v52, -v9, v57, v52
	v_fma_f32 v60, -v10, v58, v60
	v_fma_f32 v61, -v11, v59, v61
	ds_read_b128 v[56:59], v129 offset:62368
	s_waitcnt lgkmcnt(7)
	v_fma_f32 v48, -v12, v124, v48
	v_fma_f32 v52, -v13, v125, v52
	v_fma_f32 v60, -v14, v126, v60
	v_fma_f32 v61, -v15, v127, v61
	s_waitcnt lgkmcnt(6)
	v_fma_f32 v48, -v16, v120, v48
	v_fma_f32 v52, -v17, v121, v52
	v_fma_f32 v60, -v18, v122, v60
	v_fma_f32 v61, -v19, v123, v61
	s_waitcnt lgkmcnt(5)
	v_fma_f32 v48, -v20, v116, v48
	v_fma_f32 v52, -v21, v117, v52
	v_fma_f32 v60, -v22, v118, v60
	v_fma_f32 v61, -v23, v119, v61
	s_waitcnt lgkmcnt(4)
	v_fma_f32 v48, -v24, v112, v48
	v_fma_f32 v52, -v25, v113, v52
	v_fma_f32 v60, -v26, v114, v60
	v_fma_f32 v61, -v27, v115, v61
	s_waitcnt lgkmcnt(3)
	v_fma_f32 v48, -v28, v108, v48
	v_fma_f32 v52, -v29, v109, v52
	v_fma_f32 v60, -v30, v110, v60
	v_fma_f32 v61, -v31, v111, v61
	s_waitcnt lgkmcnt(2)
	v_fma_f32 v48, -v32, v104, v48
	v_fma_f32 v52, -v33, v105, v52
	v_fma_f32 v60, -v34, v106, v60
	v_fma_f32 v61, -v35, v107, v61
	s_waitcnt lgkmcnt(1)
	v_fma_f32 v48, -v36, v100, v48
	v_fma_f32 v52, -v37, v101, v52
	v_fma_f32 v60, -v38, v102, v60
	v_fma_f32 v61, -v39, v103, v61
	s_waitcnt lgkmcnt(0)
	v_fma_f32 v48, -v40, v56, v48
	v_fma_f32 v52, -v41, v57, v52
	v_fma_f32 v60, -v42, v58, v60
	v_fma_f32 v61, -v43, v59, v61
	ds_read_b128 v[56:59], v129 offset:62384
	s_waitcnt lgkmcnt(0)
	v_fma_f32 v48, -v44, v56, v48
	v_fma_f32 v52, -v45, v57, v52
	v_fma_f32 v56, -v46, v58, v60
	v_fma_f32 v57, -v47, v59, v61
	v_add_f32_e32 v48, v48, v52
	v_add_f32_e32 v52, v56, v57
	v_add_f32_e32 v48, v48, v52
	v_add_u32_e32 v52, 0x3000, v69
	ds_read_b128 v[56:59], v129 offset:62464
	ds_read2_b32 v[60:61], v52 offset0:113 offset1:178
	s_waitcnt lgkmcnt(1)
	v_mul_f32_e32 v52, v0, v56
	s_waitcnt lgkmcnt(0)
	v_fma_f32 v49, v60, v49, -v52
	v_fma_f32 v52, -v1, v57, 0
	v_fma_f32 v53, -v2, v58, 0
	v_fma_f32 v60, -v3, v59, 0
	ds_read_b128 v[100:103], v129 offset:62480
	ds_read_b128 v[56:59], v129 offset:62496
	ds_read_b128 v[124:127], v129 offset:62512
	ds_read_b128 v[120:123], v129 offset:62528
	ds_read_b128 v[116:119], v129 offset:62544
	ds_read_b128 v[112:115], v129 offset:62560
	ds_read_b128 v[108:111], v129 offset:62576
	ds_read_b128 v[104:107], v129 offset:62592
	s_waitcnt lgkmcnt(7)
	v_fma_f32 v49, -v4, v100, v49
	v_fma_f32 v52, -v5, v101, v52
	v_fma_f32 v53, -v6, v102, v53
	v_fma_f32 v60, -v7, v103, v60
	ds_read_b128 v[100:103], v129 offset:62608
	s_waitcnt lgkmcnt(7)
	v_fma_f32 v49, -v8, v56, v49
	v_fma_f32 v52, -v9, v57, v52
	v_fma_f32 v53, -v10, v58, v53
	v_fma_f32 v60, -v11, v59, v60
	ds_read_b128 v[56:59], v129 offset:62624
	s_waitcnt lgkmcnt(7)
	v_fma_f32 v49, -v12, v124, v49
	v_fma_f32 v52, -v13, v125, v52
	v_fma_f32 v53, -v14, v126, v53
	v_fma_f32 v60, -v15, v127, v60
	s_waitcnt lgkmcnt(6)
	v_fma_f32 v49, -v16, v120, v49
	v_fma_f32 v52, -v17, v121, v52
	v_fma_f32 v53, -v18, v122, v53
	v_fma_f32 v60, -v19, v123, v60
	s_waitcnt lgkmcnt(5)
	v_fma_f32 v49, -v20, v116, v49
	v_fma_f32 v52, -v21, v117, v52
	v_fma_f32 v53, -v22, v118, v53
	v_fma_f32 v60, -v23, v119, v60
	s_waitcnt lgkmcnt(4)
	v_fma_f32 v49, -v24, v112, v49
	v_fma_f32 v52, -v25, v113, v52
	v_fma_f32 v53, -v26, v114, v53
	v_fma_f32 v60, -v27, v115, v60
	s_waitcnt lgkmcnt(3)
	v_fma_f32 v49, -v28, v108, v49
	v_fma_f32 v52, -v29, v109, v52
	v_fma_f32 v53, -v30, v110, v53
	v_fma_f32 v60, -v31, v111, v60
	s_waitcnt lgkmcnt(2)
	v_fma_f32 v49, -v32, v104, v49
	v_fma_f32 v52, -v33, v105, v52
	v_fma_f32 v53, -v34, v106, v53
	v_fma_f32 v60, -v35, v107, v60
	s_waitcnt lgkmcnt(1)
	v_fma_f32 v49, -v36, v100, v49
	v_fma_f32 v52, -v37, v101, v52
	v_fma_f32 v53, -v38, v102, v53
	v_fma_f32 v60, -v39, v103, v60
	s_waitcnt lgkmcnt(0)
	v_fma_f32 v49, -v40, v56, v49
	v_fma_f32 v52, -v41, v57, v52
	v_fma_f32 v53, -v42, v58, v53
	v_fma_f32 v60, -v43, v59, v60
	ds_read_b128 v[56:59], v129 offset:62640
	s_waitcnt lgkmcnt(0)
	v_fma_f32 v52, -v45, v57, v52
	ds_read_b32 v57, v129 offset:62656
	v_fma_f32 v49, -v44, v56, v49
	v_fma_f32 v53, -v46, v58, v53
	v_fma_f32 v56, -v47, v59, v60
	s_waitcnt lgkmcnt(0)
	v_fma_f32 v49, -v48, v57, v49
	v_add_f32_e32 v49, v52, v49
	v_add_f32_e32 v52, v53, v56
	ds_read_b128 v[56:59], v129 offset:62720
	v_add_f32_e32 v49, v52, v49
	s_waitcnt lgkmcnt(0)
	v_mul_f32_e32 v52, v0, v56
	v_fma_f32 v50, v61, v50, -v52
	v_fma_f32 v52, -v1, v57, 0
	v_fma_f32 v53, -v2, v58, 0
	v_fma_f32 v54, -v3, v59, 0
	ds_read_b128 v[56:59], v129 offset:62736
	ds_read_b128 v[60:63], v129 offset:63232
	s_waitcnt lgkmcnt(1)
	v_fma_f32 v50, -v4, v56, v50
	v_fma_f32 v52, -v5, v57, v52
	v_fma_f32 v53, -v6, v58, v53
	v_fma_f32 v54, -v7, v59, v54
	ds_read_b128 v[56:59], v129 offset:62752
	ds_read_b128 v[124:127], v129 offset:62768
	ds_read_b128 v[120:123], v129 offset:62784
	ds_read_b128 v[116:119], v129 offset:62800
	ds_read_b128 v[112:115], v129 offset:62816
	ds_read_b128 v[108:111], v129 offset:62832
	ds_read_b128 v[104:107], v129 offset:62848
	ds_read_b128 v[100:103], v129 offset:62864
	s_waitcnt lgkmcnt(7)
	v_fma_f32 v50, -v8, v56, v50
	v_fma_f32 v52, -v9, v57, v52
	v_fma_f32 v53, -v10, v58, v53
	v_fma_f32 v54, -v11, v59, v54
	ds_read_b128 v[56:59], v129 offset:62880
	s_waitcnt lgkmcnt(7)
	v_fma_f32 v50, -v12, v124, v50
	v_fma_f32 v52, -v13, v125, v52
	v_fma_f32 v53, -v14, v126, v53
	v_fma_f32 v54, -v15, v127, v54
	s_waitcnt lgkmcnt(6)
	v_fma_f32 v50, -v16, v120, v50
	v_fma_f32 v52, -v17, v121, v52
	v_fma_f32 v53, -v18, v122, v53
	v_fma_f32 v54, -v19, v123, v54
	s_waitcnt lgkmcnt(5)
	v_fma_f32 v50, -v20, v116, v50
	v_fma_f32 v52, -v21, v117, v52
	v_fma_f32 v53, -v22, v118, v53
	v_fma_f32 v54, -v23, v119, v54
	s_waitcnt lgkmcnt(4)
	v_fma_f32 v50, -v24, v112, v50
	v_fma_f32 v52, -v25, v113, v52
	v_fma_f32 v53, -v26, v114, v53
	v_fma_f32 v54, -v27, v115, v54
	s_waitcnt lgkmcnt(3)
	v_fma_f32 v50, -v28, v108, v50
	v_fma_f32 v52, -v29, v109, v52
	v_fma_f32 v53, -v30, v110, v53
	v_fma_f32 v54, -v31, v111, v54
	s_waitcnt lgkmcnt(2)
	v_fma_f32 v50, -v32, v104, v50
	v_fma_f32 v52, -v33, v105, v52
	v_fma_f32 v53, -v34, v106, v53
	v_fma_f32 v54, -v35, v107, v54
	s_waitcnt lgkmcnt(1)
	v_fma_f32 v50, -v36, v100, v50
	v_fma_f32 v52, -v37, v101, v52
	v_fma_f32 v53, -v38, v102, v53
	v_fma_f32 v54, -v39, v103, v54
	s_waitcnt lgkmcnt(0)
	v_fma_f32 v50, -v40, v56, v50
	v_fma_f32 v52, -v41, v57, v52
	v_fma_f32 v53, -v42, v58, v53
	v_fma_f32 v54, -v43, v59, v54
	ds_read_b128 v[56:59], v129 offset:62896
	s_waitcnt lgkmcnt(0)
	v_fma_f32 v50, -v44, v56, v50
	v_fma_f32 v56, -v45, v57, v52
	v_fma_f32 v57, -v46, v58, v53
	ds_read_b64 v[52:53], v129 offset:62912
	v_fma_f32 v54, -v47, v59, v54
	s_waitcnt lgkmcnt(0)
	v_fma_f32 v50, -v48, v52, v50
	v_fma_f32 v52, -v49, v53, v56
	v_add_f32_e32 v50, v50, v52
	v_add_f32_e32 v52, v57, v54
	v_add_f32_e32 v50, v52, v50
	v_add_u32_e32 v52, 0x3200, v69
	ds_read2_b32 v[64:65], v52 offset0:115 offset1:180
	ds_read_b128 v[52:55], v129 offset:62976
	s_waitcnt lgkmcnt(0)
	v_mul_f32_e32 v52, v0, v52
	v_fma_f32 v51, v64, v51, -v52
	v_fma_f32 v56, -v1, v53, 0
	v_fma_f32 v57, -v2, v54, 0
	v_fma_f32 v58, -v3, v55, 0
	ds_read_b128 v[52:55], v129 offset:62992
	v_fma_f32 v64, -v2, v62, 0
	s_waitcnt lgkmcnt(0)
	v_fma_f32 v51, -v4, v52, v51
	v_fma_f32 v56, -v5, v53, v56
	v_fma_f32 v57, -v6, v54, v57
	v_fma_f32 v58, -v7, v55, v58
	ds_read_b128 v[52:55], v129 offset:63008
	ds_read_b128 v[124:127], v129 offset:63024
	ds_read_b128 v[120:123], v129 offset:63040
	ds_read_b128 v[116:119], v129 offset:63056
	ds_read_b128 v[112:115], v129 offset:63072
	ds_read_b128 v[108:111], v129 offset:63088
	ds_read_b128 v[104:107], v129 offset:63104
	ds_read_b128 v[100:103], v129 offset:63120
	s_waitcnt lgkmcnt(7)
	v_fma_f32 v51, -v8, v52, v51
	v_fma_f32 v56, -v9, v53, v56
	v_fma_f32 v57, -v10, v54, v57
	v_fma_f32 v58, -v11, v55, v58
	ds_read_b128 v[52:55], v129 offset:63136
	s_waitcnt lgkmcnt(7)
	v_fma_f32 v51, -v12, v124, v51
	v_fma_f32 v56, -v13, v125, v56
	v_fma_f32 v57, -v14, v126, v57
	v_fma_f32 v58, -v15, v127, v58
	s_waitcnt lgkmcnt(6)
	v_fma_f32 v51, -v16, v120, v51
	v_fma_f32 v56, -v17, v121, v56
	v_fma_f32 v57, -v18, v122, v57
	v_fma_f32 v58, -v19, v123, v58
	s_waitcnt lgkmcnt(5)
	v_fma_f32 v51, -v20, v116, v51
	v_fma_f32 v56, -v21, v117, v56
	v_fma_f32 v57, -v22, v118, v57
	v_fma_f32 v58, -v23, v119, v58
	s_waitcnt lgkmcnt(4)
	v_fma_f32 v51, -v24, v112, v51
	v_fma_f32 v56, -v25, v113, v56
	v_fma_f32 v57, -v26, v114, v57
	v_fma_f32 v58, -v27, v115, v58
	s_waitcnt lgkmcnt(3)
	v_fma_f32 v51, -v28, v108, v51
	v_fma_f32 v56, -v29, v109, v56
	v_fma_f32 v57, -v30, v110, v57
	v_fma_f32 v58, -v31, v111, v58
	s_waitcnt lgkmcnt(2)
	v_fma_f32 v51, -v32, v104, v51
	v_fma_f32 v56, -v33, v105, v56
	v_fma_f32 v57, -v34, v106, v57
	v_fma_f32 v58, -v35, v107, v58
	s_waitcnt lgkmcnt(1)
	v_fma_f32 v51, -v36, v100, v51
	v_fma_f32 v56, -v37, v101, v56
	v_fma_f32 v57, -v38, v102, v57
	v_fma_f32 v58, -v39, v103, v58
	s_waitcnt lgkmcnt(0)
	v_fma_f32 v51, -v40, v52, v51
	v_fma_f32 v56, -v41, v53, v56
	v_fma_f32 v57, -v42, v54, v57
	v_fma_f32 v58, -v43, v55, v58
	ds_read_b128 v[52:55], v129 offset:63152
	s_waitcnt lgkmcnt(0)
	v_fma_f32 v51, -v44, v52, v51
	v_fma_f32 v56, -v45, v53, v56
	v_fma_f32 v57, -v46, v54, v57
	ds_read_b96 v[52:54], v129 offset:63168
	v_fma_f32 v55, -v47, v55, v58
	s_waitcnt lgkmcnt(0)
	v_fma_f32 v51, -v48, v52, v51
	v_fma_f32 v52, -v49, v53, v56
	v_fma_f32 v53, -v50, v54, v57
	v_add_f32_e32 v51, v51, v52
	v_add_f32_e32 v52, v55, v53
	v_add_f32_e32 v51, v51, v52
	v_mov_b32_e32 v52, 0x104d0
	v_mov_b32_e32 v56, 0x106d0
	ds_read_b128 v[52:55], v52
	ds_read_b128 v[56:59], v56
	s_waitcnt lgkmcnt(0)
	v_cndmask_b32_e64 v52, v56, v52, s[44:45]
	v_mul_f32_e32 v56, v0, v60
	v_fma_f32 v52, v65, v52, -v56
	v_fma_f32 v56, -v1, v61, 0
	v_fma_f32 v65, -v3, v63, 0
	ds_read_b128 v[60:63], v129 offset:63248
	v_cndmask_b32_e64 v53, v57, v53, s[44:45]
	v_cndmask_b32_e64 v54, v58, v54, s[44:45]
	v_cndmask_b32_e64 v55, v59, v55, s[44:45]
	s_waitcnt lgkmcnt(0)
	v_fma_f32 v52, -v4, v60, v52
	v_fma_f32 v56, -v5, v61, v56
	v_fma_f32 v64, -v6, v62, v64
	v_fma_f32 v65, -v7, v63, v65
	ds_read_b128 v[100:103], v129 offset:63264
	ds_read_b128 v[60:63], v129 offset:63280
	ds_read_b128 v[124:127], v129 offset:63296
	ds_read_b128 v[120:123], v129 offset:63312
	ds_read_b128 v[116:119], v129 offset:63328
	ds_read_b128 v[112:115], v129 offset:63344
	ds_read_b128 v[108:111], v129 offset:63360
	ds_read_b128 v[104:107], v129 offset:63376
	s_waitcnt lgkmcnt(7)
	v_fma_f32 v52, -v8, v100, v52
	v_fma_f32 v56, -v9, v101, v56
	v_fma_f32 v64, -v10, v102, v64
	v_fma_f32 v65, -v11, v103, v65
	ds_read_b128 v[100:103], v129 offset:63392
	s_waitcnt lgkmcnt(7)
	v_fma_f32 v52, -v12, v60, v52
	v_fma_f32 v56, -v13, v61, v56
	v_fma_f32 v64, -v14, v62, v64
	v_fma_f32 v65, -v15, v63, v65
	ds_read_b128 v[60:63], v129 offset:63408
	s_waitcnt lgkmcnt(7)
	v_fma_f32 v52, -v16, v124, v52
	v_fma_f32 v56, -v17, v125, v56
	v_fma_f32 v64, -v18, v126, v64
	v_fma_f32 v65, -v19, v127, v65
	s_waitcnt lgkmcnt(6)
	v_fma_f32 v52, -v20, v120, v52
	v_fma_f32 v56, -v21, v121, v56
	v_fma_f32 v64, -v22, v122, v64
	v_fma_f32 v65, -v23, v123, v65
	s_waitcnt lgkmcnt(5)
	v_fma_f32 v52, -v24, v116, v52
	v_fma_f32 v56, -v25, v117, v56
	v_fma_f32 v64, -v26, v118, v64
	v_fma_f32 v65, -v27, v119, v65
	s_waitcnt lgkmcnt(4)
	v_fma_f32 v52, -v28, v112, v52
	v_fma_f32 v56, -v29, v113, v56
	v_fma_f32 v64, -v30, v114, v64
	v_fma_f32 v65, -v31, v115, v65
	s_waitcnt lgkmcnt(3)
	v_fma_f32 v52, -v32, v108, v52
	v_fma_f32 v56, -v33, v109, v56
	v_fma_f32 v64, -v34, v110, v64
	v_fma_f32 v65, -v35, v111, v65
	s_waitcnt lgkmcnt(2)
	v_fma_f32 v52, -v36, v104, v52
	v_fma_f32 v56, -v37, v105, v56
	v_fma_f32 v64, -v38, v106, v64
	v_fma_f32 v65, -v39, v107, v65
	s_waitcnt lgkmcnt(1)
	v_fma_f32 v52, -v40, v100, v52
	v_fma_f32 v56, -v41, v101, v56
	v_fma_f32 v64, -v42, v102, v64
	v_fma_f32 v65, -v43, v103, v65
	s_waitcnt lgkmcnt(0)
	v_fma_f32 v52, -v44, v60, v52
	v_fma_f32 v56, -v45, v61, v56
	v_fma_f32 v64, -v46, v62, v64
	v_fma_f32 v65, -v47, v63, v65
	ds_read_b128 v[60:63], v129 offset:63424
	s_waitcnt lgkmcnt(0)
	v_fma_f32 v52, -v48, v60, v52
	v_fma_f32 v56, -v49, v61, v56
	v_fma_f32 v60, -v50, v62, v64
	v_fma_f32 v61, -v51, v63, v65
	v_add_f32_e32 v52, v52, v56
	v_add_f32_e32 v56, v60, v61
	v_add_f32_e32 v52, v52, v56
	v_add_u32_e32 v56, 0x3400, v69
	ds_read_b128 v[60:63], v129 offset:63488
	ds_read2_b32 v[64:65], v56 offset0:117 offset1:182
	s_waitcnt lgkmcnt(1)
	v_mul_f32_e32 v56, v0, v60
	s_waitcnt lgkmcnt(0)
	v_fma_f32 v53, v64, v53, -v56
	v_fma_f32 v56, -v1, v61, 0
	v_fma_f32 v57, -v2, v62, 0
	v_fma_f32 v64, -v3, v63, 0
	ds_read_b128 v[104:107], v129 offset:63504
	ds_read_b128 v[100:103], v129 offset:63520
	ds_read_b128 v[60:63], v129 offset:63536
	ds_read_b128 v[124:127], v129 offset:63552
	ds_read_b128 v[120:123], v129 offset:63568
	ds_read_b128 v[116:119], v129 offset:63584
	ds_read_b128 v[112:115], v129 offset:63600
	ds_read_b128 v[108:111], v129 offset:63616
	s_waitcnt lgkmcnt(7)
	v_fma_f32 v53, -v4, v104, v53
	v_fma_f32 v56, -v5, v105, v56
	v_fma_f32 v57, -v6, v106, v57
	v_fma_f32 v64, -v7, v107, v64
	ds_read_b128 v[104:107], v129 offset:63632
	s_waitcnt lgkmcnt(7)
	v_fma_f32 v53, -v8, v100, v53
	v_fma_f32 v56, -v9, v101, v56
	v_fma_f32 v57, -v10, v102, v57
	v_fma_f32 v64, -v11, v103, v64
	ds_read_b128 v[100:103], v129 offset:63648
	s_waitcnt lgkmcnt(7)
	v_fma_f32 v53, -v12, v60, v53
	v_fma_f32 v56, -v13, v61, v56
	v_fma_f32 v57, -v14, v62, v57
	v_fma_f32 v64, -v15, v63, v64
	ds_read_b128 v[60:63], v129 offset:63664
	s_waitcnt lgkmcnt(7)
	v_fma_f32 v53, -v16, v124, v53
	v_fma_f32 v56, -v17, v125, v56
	v_fma_f32 v57, -v18, v126, v57
	v_fma_f32 v64, -v19, v127, v64
	s_waitcnt lgkmcnt(6)
	v_fma_f32 v53, -v20, v120, v53
	v_fma_f32 v56, -v21, v121, v56
	v_fma_f32 v57, -v22, v122, v57
	v_fma_f32 v64, -v23, v123, v64
	s_waitcnt lgkmcnt(5)
	v_fma_f32 v53, -v24, v116, v53
	v_fma_f32 v56, -v25, v117, v56
	v_fma_f32 v57, -v26, v118, v57
	v_fma_f32 v64, -v27, v119, v64
	s_waitcnt lgkmcnt(4)
	v_fma_f32 v53, -v28, v112, v53
	v_fma_f32 v56, -v29, v113, v56
	v_fma_f32 v57, -v30, v114, v57
	v_fma_f32 v64, -v31, v115, v64
	s_waitcnt lgkmcnt(3)
	v_fma_f32 v53, -v32, v108, v53
	v_fma_f32 v56, -v33, v109, v56
	v_fma_f32 v57, -v34, v110, v57
	v_fma_f32 v64, -v35, v111, v64
	s_waitcnt lgkmcnt(2)
	v_fma_f32 v53, -v36, v104, v53
	v_fma_f32 v56, -v37, v105, v56
	v_fma_f32 v57, -v38, v106, v57
	v_fma_f32 v64, -v39, v107, v64
	s_waitcnt lgkmcnt(1)
	v_fma_f32 v53, -v40, v100, v53
	v_fma_f32 v56, -v41, v101, v56
	v_fma_f32 v57, -v42, v102, v57
	v_fma_f32 v64, -v43, v103, v64
	s_waitcnt lgkmcnt(0)
	v_fma_f32 v53, -v44, v60, v53
	v_fma_f32 v56, -v45, v61, v56
	v_fma_f32 v57, -v46, v62, v57
	v_fma_f32 v64, -v47, v63, v64
	ds_read_b128 v[60:63], v129 offset:63680
	s_waitcnt lgkmcnt(0)
	v_fma_f32 v56, -v49, v61, v56
	ds_read_b32 v61, v129 offset:63696
	v_fma_f32 v53, -v48, v60, v53
	v_fma_f32 v57, -v50, v62, v57
	v_fma_f32 v60, -v51, v63, v64
	s_waitcnt lgkmcnt(0)
	v_fma_f32 v53, -v52, v61, v53
	v_add_f32_e32 v53, v56, v53
	v_add_f32_e32 v56, v57, v60
	ds_read_b128 v[60:63], v129 offset:63744
	v_add_f32_e32 v53, v56, v53
	s_waitcnt lgkmcnt(0)
	v_mul_f32_e32 v56, v0, v60
	v_fma_f32 v54, v65, v54, -v56
	v_fma_f32 v56, -v1, v61, 0
	v_fma_f32 v57, -v2, v62, 0
	v_fma_f32 v58, -v3, v63, 0
	ds_read_b128 v[60:63], v129 offset:63760
	ds_read_b128 v[64:67], v129 offset:64256
	s_waitcnt lgkmcnt(1)
	v_fma_f32 v54, -v4, v60, v54
	v_fma_f32 v56, -v5, v61, v56
	v_fma_f32 v57, -v6, v62, v57
	v_fma_f32 v58, -v7, v63, v58
	ds_read_b128 v[100:103], v129 offset:63776
	ds_read_b128 v[60:63], v129 offset:63792
	ds_read_b128 v[124:127], v129 offset:63808
	ds_read_b128 v[120:123], v129 offset:63824
	ds_read_b128 v[116:119], v129 offset:63840
	ds_read_b128 v[112:115], v129 offset:63856
	ds_read_b128 v[108:111], v129 offset:63872
	ds_read_b128 v[104:107], v129 offset:63888
	s_waitcnt lgkmcnt(7)
	v_fma_f32 v54, -v8, v100, v54
	v_fma_f32 v56, -v9, v101, v56
	v_fma_f32 v57, -v10, v102, v57
	v_fma_f32 v58, -v11, v103, v58
	ds_read_b128 v[100:103], v129 offset:63904
	s_waitcnt lgkmcnt(7)
	v_fma_f32 v54, -v12, v60, v54
	v_fma_f32 v56, -v13, v61, v56
	v_fma_f32 v57, -v14, v62, v57
	v_fma_f32 v58, -v15, v63, v58
	ds_read_b128 v[60:63], v129 offset:63920
	s_waitcnt lgkmcnt(7)
	v_fma_f32 v54, -v16, v124, v54
	v_fma_f32 v56, -v17, v125, v56
	v_fma_f32 v57, -v18, v126, v57
	v_fma_f32 v58, -v19, v127, v58
	s_waitcnt lgkmcnt(6)
	v_fma_f32 v54, -v20, v120, v54
	v_fma_f32 v56, -v21, v121, v56
	v_fma_f32 v57, -v22, v122, v57
	v_fma_f32 v58, -v23, v123, v58
	s_waitcnt lgkmcnt(5)
	v_fma_f32 v54, -v24, v116, v54
	v_fma_f32 v56, -v25, v117, v56
	v_fma_f32 v57, -v26, v118, v57
	v_fma_f32 v58, -v27, v119, v58
	s_waitcnt lgkmcnt(4)
	v_fma_f32 v54, -v28, v112, v54
	v_fma_f32 v56, -v29, v113, v56
	v_fma_f32 v57, -v30, v114, v57
	v_fma_f32 v58, -v31, v115, v58
	s_waitcnt lgkmcnt(3)
	v_fma_f32 v54, -v32, v108, v54
	v_fma_f32 v56, -v33, v109, v56
	v_fma_f32 v57, -v34, v110, v57
	v_fma_f32 v58, -v35, v111, v58
	s_waitcnt lgkmcnt(2)
	v_fma_f32 v54, -v36, v104, v54
	v_fma_f32 v56, -v37, v105, v56
	v_fma_f32 v57, -v38, v106, v57
	v_fma_f32 v58, -v39, v107, v58
	s_waitcnt lgkmcnt(1)
	v_fma_f32 v54, -v40, v100, v54
	v_fma_f32 v56, -v41, v101, v56
	v_fma_f32 v57, -v42, v102, v57
	v_fma_f32 v58, -v43, v103, v58
	s_waitcnt lgkmcnt(0)
	v_fma_f32 v54, -v44, v60, v54
	v_fma_f32 v56, -v45, v61, v56
	v_fma_f32 v57, -v46, v62, v57
	v_fma_f32 v58, -v47, v63, v58
	ds_read_b128 v[60:63], v129 offset:63936
	s_waitcnt lgkmcnt(0)
	v_fma_f32 v54, -v48, v60, v54
	v_fma_f32 v60, -v49, v61, v56
	v_fma_f32 v61, -v50, v62, v57
	ds_read_b64 v[56:57], v129 offset:63952
	v_fma_f32 v58, -v51, v63, v58
	s_waitcnt lgkmcnt(0)
	v_fma_f32 v54, -v52, v56, v54
	v_fma_f32 v56, -v53, v57, v60
	v_add_f32_e32 v54, v54, v56
	v_add_f32_e32 v56, v61, v58
	v_add_f32_e32 v54, v56, v54
	v_add_u32_e32 v56, 0x3600, v69
	ds_read2_b32 v[70:71], v56 offset0:119 offset1:184
	ds_read_b128 v[56:59], v129 offset:64000
	s_waitcnt lgkmcnt(0)
	v_mul_f32_e32 v56, v0, v56
	v_fma_f32 v55, v70, v55, -v56
	v_fma_f32 v60, -v1, v57, 0
	v_fma_f32 v61, -v2, v58, 0
	v_fma_f32 v62, -v3, v59, 0
	ds_read_b128 v[56:59], v129 offset:64016
	v_fma_f32 v70, -v2, v66, 0
	s_waitcnt lgkmcnt(0)
	v_fma_f32 v55, -v4, v56, v55
	v_fma_f32 v60, -v5, v57, v60
	v_fma_f32 v61, -v6, v58, v61
	v_fma_f32 v62, -v7, v59, v62
	ds_read_b128 v[100:103], v129 offset:64032
	ds_read_b128 v[56:59], v129 offset:64048
	ds_read_b128 v[124:127], v129 offset:64064
	ds_read_b128 v[120:123], v129 offset:64080
	ds_read_b128 v[116:119], v129 offset:64096
	ds_read_b128 v[112:115], v129 offset:64112
	ds_read_b128 v[108:111], v129 offset:64128
	ds_read_b128 v[104:107], v129 offset:64144
	s_waitcnt lgkmcnt(7)
	v_fma_f32 v55, -v8, v100, v55
	v_fma_f32 v60, -v9, v101, v60
	v_fma_f32 v61, -v10, v102, v61
	v_fma_f32 v62, -v11, v103, v62
	ds_read_b128 v[100:103], v129 offset:64160
	s_waitcnt lgkmcnt(7)
	v_fma_f32 v55, -v12, v56, v55
	v_fma_f32 v60, -v13, v57, v60
	v_fma_f32 v61, -v14, v58, v61
	v_fma_f32 v62, -v15, v59, v62
	ds_read_b128 v[56:59], v129 offset:64176
	s_waitcnt lgkmcnt(7)
	v_fma_f32 v55, -v16, v124, v55
	v_fma_f32 v60, -v17, v125, v60
	v_fma_f32 v61, -v18, v126, v61
	v_fma_f32 v62, -v19, v127, v62
	s_waitcnt lgkmcnt(6)
	v_fma_f32 v55, -v20, v120, v55
	v_fma_f32 v60, -v21, v121, v60
	v_fma_f32 v61, -v22, v122, v61
	v_fma_f32 v62, -v23, v123, v62
	s_waitcnt lgkmcnt(5)
	v_fma_f32 v55, -v24, v116, v55
	v_fma_f32 v60, -v25, v117, v60
	v_fma_f32 v61, -v26, v118, v61
	v_fma_f32 v62, -v27, v119, v62
	s_waitcnt lgkmcnt(4)
	v_fma_f32 v55, -v28, v112, v55
	v_fma_f32 v60, -v29, v113, v60
	v_fma_f32 v61, -v30, v114, v61
	v_fma_f32 v62, -v31, v115, v62
	s_waitcnt lgkmcnt(3)
	v_fma_f32 v55, -v32, v108, v55
	v_fma_f32 v60, -v33, v109, v60
	v_fma_f32 v61, -v34, v110, v61
	v_fma_f32 v62, -v35, v111, v62
	s_waitcnt lgkmcnt(2)
	v_fma_f32 v55, -v36, v104, v55
	v_fma_f32 v60, -v37, v105, v60
	v_fma_f32 v61, -v38, v106, v61
	v_fma_f32 v62, -v39, v107, v62
	s_waitcnt lgkmcnt(1)
	v_fma_f32 v55, -v40, v100, v55
	v_fma_f32 v60, -v41, v101, v60
	v_fma_f32 v61, -v42, v102, v61
	v_fma_f32 v62, -v43, v103, v62
	s_waitcnt lgkmcnt(0)
	v_fma_f32 v55, -v44, v56, v55
	v_fma_f32 v60, -v45, v57, v60
	v_fma_f32 v61, -v46, v58, v61
	v_fma_f32 v62, -v47, v59, v62
	ds_read_b128 v[56:59], v129 offset:64192
	s_waitcnt lgkmcnt(0)
	v_fma_f32 v55, -v48, v56, v55
	v_fma_f32 v60, -v49, v57, v60
	v_fma_f32 v61, -v50, v58, v61
	ds_read_b96 v[56:58], v129 offset:64208
	v_fma_f32 v59, -v51, v59, v62
	s_waitcnt lgkmcnt(0)
	v_fma_f32 v55, -v52, v56, v55
	v_fma_f32 v56, -v53, v57, v60
	v_fma_f32 v57, -v54, v58, v61
	v_add_f32_e32 v55, v55, v56
	v_add_f32_e32 v56, v59, v57
	v_add_f32_e32 v55, v55, v56
	v_mov_b32_e32 v56, 0x104e0
	v_mov_b32_e32 v60, 0x106e0
	ds_read_b128 v[56:59], v56
	ds_read_b128 v[60:63], v60
	s_waitcnt lgkmcnt(0)
	v_cndmask_b32_e64 v56, v60, v56, s[44:45]
	v_mul_f32_e32 v60, v0, v64
	v_fma_f32 v56, v71, v56, -v60
	v_fma_f32 v60, -v1, v65, 0
	v_fma_f32 v71, -v3, v67, 0
	ds_read_b128 v[64:67], v129 offset:64272
	v_cndmask_b32_e64 v57, v61, v57, s[44:45]
	v_cndmask_b32_e64 v58, v62, v58, s[44:45]
	v_cndmask_b32_e64 v59, v63, v59, s[44:45]
	s_waitcnt lgkmcnt(0)
	v_fma_f32 v56, -v4, v64, v56
	v_fma_f32 v60, -v5, v65, v60
	v_fma_f32 v70, -v6, v66, v70
	v_fma_f32 v71, -v7, v67, v71
	ds_read_b128 v[104:107], v129 offset:64288
	ds_read_b128 v[100:103], v129 offset:64304
	ds_read_b128 v[64:67], v129 offset:64320
	ds_read_b128 v[124:127], v129 offset:64336
	ds_read_b128 v[120:123], v129 offset:64352
	ds_read_b128 v[116:119], v129 offset:64368
	ds_read_b128 v[112:115], v129 offset:64384
	ds_read_b128 v[108:111], v129 offset:64400
	s_waitcnt lgkmcnt(7)
	v_fma_f32 v56, -v8, v104, v56
	v_fma_f32 v60, -v9, v105, v60
	v_fma_f32 v70, -v10, v106, v70
	v_fma_f32 v71, -v11, v107, v71
	ds_read_b128 v[104:107], v129 offset:64416
	s_waitcnt lgkmcnt(7)
	v_fma_f32 v56, -v12, v100, v56
	v_fma_f32 v60, -v13, v101, v60
	v_fma_f32 v70, -v14, v102, v70
	v_fma_f32 v71, -v15, v103, v71
	ds_read_b128 v[100:103], v129 offset:64432
	s_waitcnt lgkmcnt(7)
	v_fma_f32 v56, -v16, v64, v56
	v_fma_f32 v60, -v17, v65, v60
	v_fma_f32 v70, -v18, v66, v70
	v_fma_f32 v71, -v19, v67, v71
	ds_read_b128 v[64:67], v129 offset:64448
	s_waitcnt lgkmcnt(7)
	v_fma_f32 v56, -v20, v124, v56
	v_fma_f32 v60, -v21, v125, v60
	v_fma_f32 v70, -v22, v126, v70
	v_fma_f32 v71, -v23, v127, v71
	s_waitcnt lgkmcnt(6)
	v_fma_f32 v56, -v24, v120, v56
	v_fma_f32 v60, -v25, v121, v60
	v_fma_f32 v70, -v26, v122, v70
	v_fma_f32 v71, -v27, v123, v71
	s_waitcnt lgkmcnt(5)
	v_fma_f32 v56, -v28, v116, v56
	v_fma_f32 v60, -v29, v117, v60
	v_fma_f32 v70, -v30, v118, v70
	v_fma_f32 v71, -v31, v119, v71
	s_waitcnt lgkmcnt(4)
	v_fma_f32 v56, -v32, v112, v56
	v_fma_f32 v60, -v33, v113, v60
	v_fma_f32 v70, -v34, v114, v70
	v_fma_f32 v71, -v35, v115, v71
	s_waitcnt lgkmcnt(3)
	v_fma_f32 v56, -v36, v108, v56
	v_fma_f32 v60, -v37, v109, v60
	v_fma_f32 v70, -v38, v110, v70
	v_fma_f32 v71, -v39, v111, v71
	s_waitcnt lgkmcnt(2)
	v_fma_f32 v56, -v40, v104, v56
	v_fma_f32 v60, -v41, v105, v60
	v_fma_f32 v70, -v42, v106, v70
	v_fma_f32 v71, -v43, v107, v71
	s_waitcnt lgkmcnt(1)
	v_fma_f32 v56, -v44, v100, v56
	v_fma_f32 v60, -v45, v101, v60
	v_fma_f32 v70, -v46, v102, v70
	v_fma_f32 v71, -v47, v103, v71
	s_waitcnt lgkmcnt(0)
	v_fma_f32 v56, -v48, v64, v56
	v_fma_f32 v60, -v49, v65, v60
	v_fma_f32 v70, -v50, v66, v70
	v_fma_f32 v71, -v51, v67, v71
	ds_read_b128 v[64:67], v129 offset:64464
	s_waitcnt lgkmcnt(0)
	v_fma_f32 v56, -v52, v64, v56
	v_fma_f32 v60, -v53, v65, v60
	v_fma_f32 v64, -v54, v66, v70
	v_fma_f32 v65, -v55, v67, v71
	v_add_f32_e32 v56, v56, v60
	v_add_f32_e32 v60, v64, v65
	v_add_f32_e32 v56, v56, v60
	v_add_u32_e32 v60, 0x3800, v69
	ds_read_b128 v[64:67], v129 offset:64512
	ds_read2_b32 v[70:71], v60 offset0:121 offset1:186
	s_waitcnt lgkmcnt(1)
	v_mul_f32_e32 v60, v0, v64
	s_waitcnt lgkmcnt(0)
	v_fma_f32 v57, v70, v57, -v60
	v_fma_f32 v60, -v1, v65, 0
	v_fma_f32 v61, -v2, v66, 0
	v_fma_f32 v70, -v3, v67, 0
	ds_read_b128 v[108:111], v129 offset:64528
	ds_read_b128 v[104:107], v129 offset:64544
	ds_read_b128 v[100:103], v129 offset:64560
	ds_read_b128 v[64:67], v129 offset:64576
	ds_read_b128 v[124:127], v129 offset:64592
	ds_read_b128 v[120:123], v129 offset:64608
	ds_read_b128 v[116:119], v129 offset:64624
	ds_read_b128 v[112:115], v129 offset:64640
	s_waitcnt lgkmcnt(7)
	v_fma_f32 v57, -v4, v108, v57
	v_fma_f32 v60, -v5, v109, v60
	v_fma_f32 v61, -v6, v110, v61
	v_fma_f32 v70, -v7, v111, v70
	ds_read_b128 v[108:111], v129 offset:64656
	s_waitcnt lgkmcnt(7)
	v_fma_f32 v57, -v8, v104, v57
	v_fma_f32 v60, -v9, v105, v60
	v_fma_f32 v61, -v10, v106, v61
	v_fma_f32 v70, -v11, v107, v70
	ds_read_b128 v[104:107], v129 offset:64672
	s_waitcnt lgkmcnt(7)
	v_fma_f32 v57, -v12, v100, v57
	v_fma_f32 v60, -v13, v101, v60
	v_fma_f32 v61, -v14, v102, v61
	v_fma_f32 v70, -v15, v103, v70
	ds_read_b128 v[100:103], v129 offset:64688
	s_waitcnt lgkmcnt(7)
	v_fma_f32 v57, -v16, v64, v57
	v_fma_f32 v60, -v17, v65, v60
	v_fma_f32 v61, -v18, v66, v61
	v_fma_f32 v70, -v19, v67, v70
	ds_read_b128 v[64:67], v129 offset:64704
	s_waitcnt lgkmcnt(7)
	v_fma_f32 v57, -v20, v124, v57
	v_fma_f32 v60, -v21, v125, v60
	v_fma_f32 v61, -v22, v126, v61
	v_fma_f32 v70, -v23, v127, v70
	s_waitcnt lgkmcnt(6)
	v_fma_f32 v57, -v24, v120, v57
	v_fma_f32 v60, -v25, v121, v60
	v_fma_f32 v61, -v26, v122, v61
	v_fma_f32 v70, -v27, v123, v70
	s_waitcnt lgkmcnt(5)
	v_fma_f32 v57, -v28, v116, v57
	v_fma_f32 v60, -v29, v117, v60
	v_fma_f32 v61, -v30, v118, v61
	v_fma_f32 v70, -v31, v119, v70
	s_waitcnt lgkmcnt(4)
	v_fma_f32 v57, -v32, v112, v57
	v_fma_f32 v60, -v33, v113, v60
	v_fma_f32 v61, -v34, v114, v61
	v_fma_f32 v70, -v35, v115, v70
	s_waitcnt lgkmcnt(3)
	v_fma_f32 v57, -v36, v108, v57
	v_fma_f32 v60, -v37, v109, v60
	v_fma_f32 v61, -v38, v110, v61
	v_fma_f32 v70, -v39, v111, v70
	s_waitcnt lgkmcnt(2)
	v_fma_f32 v57, -v40, v104, v57
	v_fma_f32 v60, -v41, v105, v60
	v_fma_f32 v61, -v42, v106, v61
	v_fma_f32 v70, -v43, v107, v70
	s_waitcnt lgkmcnt(1)
	v_fma_f32 v57, -v44, v100, v57
	v_fma_f32 v60, -v45, v101, v60
	v_fma_f32 v61, -v46, v102, v61
	v_fma_f32 v70, -v47, v103, v70
	s_waitcnt lgkmcnt(0)
	v_fma_f32 v57, -v48, v64, v57
	v_fma_f32 v60, -v49, v65, v60
	v_fma_f32 v61, -v50, v66, v61
	v_fma_f32 v70, -v51, v67, v70
	ds_read_b128 v[64:67], v129 offset:64720
	s_waitcnt lgkmcnt(0)
	v_fma_f32 v60, -v53, v65, v60
	ds_read_b32 v65, v129 offset:64736
	v_fma_f32 v57, -v52, v64, v57
	v_fma_f32 v61, -v54, v66, v61
	v_fma_f32 v64, -v55, v67, v70
	s_waitcnt lgkmcnt(0)
	v_fma_f32 v57, -v56, v65, v57
	v_add_f32_e32 v57, v60, v57
	v_add_f32_e32 v60, v61, v64
	ds_read_b128 v[64:67], v129 offset:64768
	v_add_f32_e32 v57, v60, v57
	s_waitcnt lgkmcnt(0)
	v_mul_f32_e32 v60, v0, v64
	v_fma_f32 v58, v71, v58, -v60
	v_fma_f32 v60, -v1, v65, 0
	v_fma_f32 v61, -v2, v66, 0
	v_fma_f32 v62, -v3, v67, 0
	ds_read_b128 v[64:67], v129 offset:64784
	ds_read_b128 v[70:73], v129 offset:65280
	s_waitcnt lgkmcnt(1)
	v_fma_f32 v58, -v4, v64, v58
	v_fma_f32 v60, -v5, v65, v60
	v_fma_f32 v61, -v6, v66, v61
	v_fma_f32 v62, -v7, v67, v62
	ds_read_b128 v[104:107], v129 offset:64800
	ds_read_b128 v[100:103], v129 offset:64816
	ds_read_b128 v[64:67], v129 offset:64832
	ds_read_b128 v[124:127], v129 offset:64848
	ds_read_b128 v[120:123], v129 offset:64864
	ds_read_b128 v[116:119], v129 offset:64880
	ds_read_b128 v[112:115], v129 offset:64896
	ds_read_b128 v[108:111], v129 offset:64912
	s_waitcnt lgkmcnt(7)
	v_fma_f32 v58, -v8, v104, v58
	v_fma_f32 v60, -v9, v105, v60
	v_fma_f32 v61, -v10, v106, v61
	v_fma_f32 v62, -v11, v107, v62
	ds_read_b128 v[104:107], v129 offset:64928
	s_waitcnt lgkmcnt(7)
	v_fma_f32 v58, -v12, v100, v58
	v_fma_f32 v60, -v13, v101, v60
	v_fma_f32 v61, -v14, v102, v61
	v_fma_f32 v62, -v15, v103, v62
	ds_read_b128 v[100:103], v129 offset:64944
	s_waitcnt lgkmcnt(7)
	v_fma_f32 v58, -v16, v64, v58
	v_fma_f32 v60, -v17, v65, v60
	v_fma_f32 v61, -v18, v66, v61
	v_fma_f32 v62, -v19, v67, v62
	ds_read_b128 v[64:67], v129 offset:64960
	s_waitcnt lgkmcnt(7)
	v_fma_f32 v58, -v20, v124, v58
	v_fma_f32 v60, -v21, v125, v60
	v_fma_f32 v61, -v22, v126, v61
	v_fma_f32 v62, -v23, v127, v62
	s_waitcnt lgkmcnt(6)
	v_fma_f32 v58, -v24, v120, v58
	v_fma_f32 v60, -v25, v121, v60
	v_fma_f32 v61, -v26, v122, v61
	v_fma_f32 v62, -v27, v123, v62
	s_waitcnt lgkmcnt(5)
	v_fma_f32 v58, -v28, v116, v58
	v_fma_f32 v60, -v29, v117, v60
	v_fma_f32 v61, -v30, v118, v61
	v_fma_f32 v62, -v31, v119, v62
	s_waitcnt lgkmcnt(4)
	v_fma_f32 v58, -v32, v112, v58
	v_fma_f32 v60, -v33, v113, v60
	v_fma_f32 v61, -v34, v114, v61
	v_fma_f32 v62, -v35, v115, v62
	s_waitcnt lgkmcnt(3)
	v_fma_f32 v58, -v36, v108, v58
	v_fma_f32 v60, -v37, v109, v60
	v_fma_f32 v61, -v38, v110, v61
	v_fma_f32 v62, -v39, v111, v62
	s_waitcnt lgkmcnt(2)
	v_fma_f32 v58, -v40, v104, v58
	v_fma_f32 v60, -v41, v105, v60
	v_fma_f32 v61, -v42, v106, v61
	v_fma_f32 v62, -v43, v107, v62
	s_waitcnt lgkmcnt(1)
	v_fma_f32 v58, -v44, v100, v58
	v_fma_f32 v60, -v45, v101, v60
	v_fma_f32 v61, -v46, v102, v61
	v_fma_f32 v62, -v47, v103, v62
	s_waitcnt lgkmcnt(0)
	v_fma_f32 v58, -v48, v64, v58
	v_fma_f32 v60, -v49, v65, v60
	v_fma_f32 v61, -v50, v66, v61
	v_fma_f32 v62, -v51, v67, v62
	ds_read_b128 v[64:67], v129 offset:64976
	s_waitcnt lgkmcnt(0)
	v_fma_f32 v58, -v52, v64, v58
	v_fma_f32 v64, -v53, v65, v60
	v_fma_f32 v65, -v54, v66, v61
	ds_read_b64 v[60:61], v129 offset:64992
	v_fma_f32 v62, -v55, v67, v62
	s_waitcnt lgkmcnt(0)
	v_fma_f32 v58, -v56, v60, v58
	v_fma_f32 v60, -v57, v61, v64
	v_add_f32_e32 v58, v58, v60
	v_add_f32_e32 v60, v65, v62
	v_add_f32_e32 v58, v60, v58
	v_add_u32_e32 v60, 0x3a00, v69
	ds_read2_b32 v[74:75], v60 offset0:123 offset1:188
	ds_read_b128 v[60:63], v129 offset:65024
	s_waitcnt lgkmcnt(0)
	v_mul_f32_e32 v60, v0, v60
	v_fma_f32 v59, v74, v59, -v60
	v_fma_f32 v64, -v1, v61, 0
	v_fma_f32 v65, -v2, v62, 0
	v_fma_f32 v66, -v3, v63, 0
	ds_read_b128 v[60:63], v129 offset:65040
	v_fma_f32 v74, -v2, v72, 0
	s_waitcnt lgkmcnt(0)
	v_fma_f32 v59, -v4, v60, v59
	v_fma_f32 v64, -v5, v61, v64
	v_fma_f32 v65, -v6, v62, v65
	v_fma_f32 v66, -v7, v63, v66
	ds_read_b128 v[104:107], v129 offset:65056
	ds_read_b128 v[100:103], v129 offset:65072
	ds_read_b128 v[60:63], v129 offset:65088
	ds_read_b128 v[124:127], v129 offset:65104
	ds_read_b128 v[120:123], v129 offset:65120
	ds_read_b128 v[116:119], v129 offset:65136
	ds_read_b128 v[112:115], v129 offset:65152
	ds_read_b128 v[108:111], v129 offset:65168
	s_waitcnt lgkmcnt(7)
	v_fma_f32 v59, -v8, v104, v59
	v_fma_f32 v64, -v9, v105, v64
	v_fma_f32 v65, -v10, v106, v65
	v_fma_f32 v66, -v11, v107, v66
	ds_read_b128 v[104:107], v129 offset:65184
	s_waitcnt lgkmcnt(7)
	v_fma_f32 v59, -v12, v100, v59
	v_fma_f32 v64, -v13, v101, v64
	v_fma_f32 v65, -v14, v102, v65
	v_fma_f32 v66, -v15, v103, v66
	ds_read_b128 v[100:103], v129 offset:65200
	s_waitcnt lgkmcnt(7)
	v_fma_f32 v59, -v16, v60, v59
	v_fma_f32 v64, -v17, v61, v64
	v_fma_f32 v65, -v18, v62, v65
	v_fma_f32 v66, -v19, v63, v66
	ds_read_b128 v[60:63], v129 offset:65216
	s_waitcnt lgkmcnt(7)
	v_fma_f32 v59, -v20, v124, v59
	v_fma_f32 v64, -v21, v125, v64
	v_fma_f32 v65, -v22, v126, v65
	v_fma_f32 v66, -v23, v127, v66
	s_waitcnt lgkmcnt(6)
	v_fma_f32 v59, -v24, v120, v59
	v_fma_f32 v64, -v25, v121, v64
	v_fma_f32 v65, -v26, v122, v65
	v_fma_f32 v66, -v27, v123, v66
	s_waitcnt lgkmcnt(5)
	v_fma_f32 v59, -v28, v116, v59
	v_fma_f32 v64, -v29, v117, v64
	v_fma_f32 v65, -v30, v118, v65
	v_fma_f32 v66, -v31, v119, v66
	s_waitcnt lgkmcnt(4)
	v_fma_f32 v59, -v32, v112, v59
	v_fma_f32 v64, -v33, v113, v64
	v_fma_f32 v65, -v34, v114, v65
	v_fma_f32 v66, -v35, v115, v66
	s_waitcnt lgkmcnt(3)
	v_fma_f32 v59, -v36, v108, v59
	v_fma_f32 v64, -v37, v109, v64
	v_fma_f32 v65, -v38, v110, v65
	v_fma_f32 v66, -v39, v111, v66
	s_waitcnt lgkmcnt(2)
	v_fma_f32 v59, -v40, v104, v59
	v_fma_f32 v64, -v41, v105, v64
	v_fma_f32 v65, -v42, v106, v65
	v_fma_f32 v66, -v43, v107, v66
	s_waitcnt lgkmcnt(1)
	v_fma_f32 v59, -v44, v100, v59
	v_fma_f32 v64, -v45, v101, v64
	v_fma_f32 v65, -v46, v102, v65
	v_fma_f32 v66, -v47, v103, v66
	s_waitcnt lgkmcnt(0)
	v_fma_f32 v59, -v48, v60, v59
	v_fma_f32 v64, -v49, v61, v64
	v_fma_f32 v65, -v50, v62, v65
	v_fma_f32 v66, -v51, v63, v66
	ds_read_b128 v[60:63], v129 offset:65232
	s_waitcnt lgkmcnt(0)
	v_fma_f32 v59, -v52, v60, v59
	v_fma_f32 v64, -v53, v61, v64
	v_fma_f32 v65, -v54, v62, v65
	ds_read_b96 v[60:62], v129 offset:65248
	v_fma_f32 v63, -v55, v63, v66
	s_waitcnt lgkmcnt(0)
	v_fma_f32 v59, -v56, v60, v59
	v_fma_f32 v60, -v57, v61, v64
	v_fma_f32 v61, -v58, v62, v65
	v_add_f32_e32 v59, v59, v60
	v_add_f32_e32 v60, v63, v61
	v_add_f32_e32 v59, v59, v60
	v_mov_b32_e32 v60, 0x104f0
	v_mov_b32_e32 v64, 0x106f0
	ds_read_b128 v[60:63], v60
	ds_read_b128 v[64:67], v64
	s_waitcnt lgkmcnt(0)
	v_cndmask_b32_e64 v60, v64, v60, s[44:45]
	v_mul_f32_e32 v64, v0, v70
	v_fma_f32 v60, v75, v60, -v64
	v_fma_f32 v64, -v1, v71, 0
	v_fma_f32 v75, -v3, v73, 0
	ds_read_b128 v[70:73], v129 offset:65296
	v_cndmask_b32_e64 v61, v65, v61, s[44:45]
	v_cndmask_b32_e64 v62, v66, v62, s[44:45]
	v_cndmask_b32_e64 v63, v67, v63, s[44:45]
	s_waitcnt lgkmcnt(0)
	v_fma_f32 v60, -v4, v70, v60
	v_fma_f32 v64, -v5, v71, v64
	v_fma_f32 v74, -v6, v72, v74
	v_fma_f32 v75, -v7, v73, v75
	ds_read_b128 v[108:111], v129 offset:65312
	ds_read_b128 v[104:107], v129 offset:65328
	ds_read_b128 v[100:103], v129 offset:65344
	ds_read_b128 v[70:73], v129 offset:65360
	ds_read_b128 v[124:127], v129 offset:65376
	ds_read_b128 v[120:123], v129 offset:65392
	ds_read_b128 v[116:119], v129 offset:65408
	ds_read_b128 v[112:115], v129 offset:65424
	s_waitcnt lgkmcnt(7)
	v_fma_f32 v60, -v8, v108, v60
	v_fma_f32 v64, -v9, v109, v64
	v_fma_f32 v74, -v10, v110, v74
	v_fma_f32 v75, -v11, v111, v75
	ds_read_b128 v[108:111], v129 offset:65440
	s_waitcnt lgkmcnt(7)
	v_fma_f32 v60, -v12, v104, v60
	v_fma_f32 v64, -v13, v105, v64
	v_fma_f32 v74, -v14, v106, v74
	v_fma_f32 v75, -v15, v107, v75
	ds_read_b128 v[104:107], v129 offset:65456
	s_waitcnt lgkmcnt(7)
	v_fma_f32 v60, -v16, v100, v60
	v_fma_f32 v64, -v17, v101, v64
	v_fma_f32 v74, -v18, v102, v74
	v_fma_f32 v75, -v19, v103, v75
	ds_read_b128 v[100:103], v129 offset:65472
	s_waitcnt lgkmcnt(7)
	v_fma_f32 v60, -v20, v70, v60
	v_fma_f32 v64, -v21, v71, v64
	v_fma_f32 v74, -v22, v72, v74
	v_fma_f32 v75, -v23, v73, v75
	ds_read_b128 v[70:73], v129 offset:65488
	s_waitcnt lgkmcnt(7)
	v_fma_f32 v60, -v24, v124, v60
	v_fma_f32 v64, -v25, v125, v64
	v_fma_f32 v74, -v26, v126, v74
	v_fma_f32 v75, -v27, v127, v75
	s_waitcnt lgkmcnt(6)
	v_fma_f32 v60, -v28, v120, v60
	v_fma_f32 v64, -v29, v121, v64
	v_fma_f32 v74, -v30, v122, v74
	v_fma_f32 v75, -v31, v123, v75
	s_waitcnt lgkmcnt(5)
	v_fma_f32 v60, -v32, v116, v60
	v_fma_f32 v64, -v33, v117, v64
	v_fma_f32 v74, -v34, v118, v74
	v_fma_f32 v75, -v35, v119, v75
	s_waitcnt lgkmcnt(4)
	v_fma_f32 v60, -v36, v112, v60
	v_fma_f32 v64, -v37, v113, v64
	v_fma_f32 v74, -v38, v114, v74
	v_fma_f32 v75, -v39, v115, v75
	s_waitcnt lgkmcnt(3)
	v_fma_f32 v60, -v40, v108, v60
	v_fma_f32 v64, -v41, v109, v64
	v_fma_f32 v74, -v42, v110, v74
	v_fma_f32 v75, -v43, v111, v75
	s_waitcnt lgkmcnt(2)
	v_fma_f32 v60, -v44, v104, v60
	v_fma_f32 v64, -v45, v105, v64
	v_fma_f32 v74, -v46, v106, v74
	v_fma_f32 v75, -v47, v107, v75
	s_waitcnt lgkmcnt(1)
	v_fma_f32 v60, -v48, v100, v60
	v_fma_f32 v64, -v49, v101, v64
	v_fma_f32 v74, -v50, v102, v74
	v_fma_f32 v75, -v51, v103, v75
	s_waitcnt lgkmcnt(0)
	v_fma_f32 v60, -v52, v70, v60
	v_fma_f32 v64, -v53, v71, v64
	v_fma_f32 v74, -v54, v72, v74
	v_fma_f32 v75, -v55, v73, v75
	ds_read_b128 v[70:73], v129 offset:65504
	s_waitcnt lgkmcnt(0)
	v_fma_f32 v60, -v56, v70, v60
	v_fma_f32 v64, -v57, v71, v64
	v_fma_f32 v70, -v58, v72, v74
	v_fma_f32 v71, -v59, v73, v75
	v_add_f32_e32 v60, v60, v64
	v_add_f32_e32 v64, v70, v71
	v_add_f32_e32 v60, v60, v64
	v_add_u32_e32 v64, 0x3c00, v69
	ds_read2_b32 v[74:75], v64 offset0:125 offset1:190
	v_mov_b32_e32 v64, 0x10000
	ds_read_b128 v[70:73], v64
	ds_read_b32 v69, v69 offset:16380
	s_waitcnt lgkmcnt(1)
	v_mul_f32_e32 v64, v0, v70
	v_mov_b32_e32 v70, 0x10010
	v_fma_f32 v61, v74, v61, -v64
	v_fma_f32 v64, -v1, v71, 0
	v_fma_f32 v65, -v2, v72, 0
	v_fma_f32 v74, -v3, v73, 0
	ds_read_b128 v[70:73], v70
	s_waitcnt lgkmcnt(0)
	v_fma_f32 v61, -v4, v70, v61
	v_mov_b32_e32 v70, 0x10020
	v_fma_f32 v64, -v5, v71, v64
	v_fma_f32 v65, -v6, v72, v65
	v_fma_f32 v74, -v7, v73, v74
	ds_read_b128 v[70:73], v70
	s_waitcnt lgkmcnt(0)
	v_fma_f32 v61, -v8, v70, v61
	v_mov_b32_e32 v70, 0x10030
	v_fma_f32 v64, -v9, v71, v64
	v_fma_f32 v65, -v10, v72, v65
	v_fma_f32 v74, -v11, v73, v74
	ds_read_b128 v[70:73], v70
	s_waitcnt lgkmcnt(0)
	v_fma_f32 v61, -v12, v70, v61
	v_mov_b32_e32 v70, 0x10040
	v_fma_f32 v64, -v13, v71, v64
	v_fma_f32 v65, -v14, v72, v65
	v_fma_f32 v74, -v15, v73, v74
	ds_read_b128 v[70:73], v70
	s_waitcnt lgkmcnt(0)
	v_fma_f32 v61, -v16, v70, v61
	v_mov_b32_e32 v70, 0x10050
	v_fma_f32 v64, -v17, v71, v64
	v_fma_f32 v65, -v18, v72, v65
	v_fma_f32 v74, -v19, v73, v74
	ds_read_b128 v[70:73], v70
	s_waitcnt lgkmcnt(0)
	v_fma_f32 v61, -v20, v70, v61
	v_mov_b32_e32 v70, 0x10060
	v_fma_f32 v64, -v21, v71, v64
	v_fma_f32 v65, -v22, v72, v65
	v_fma_f32 v74, -v23, v73, v74
	ds_read_b128 v[70:73], v70
	s_waitcnt lgkmcnt(0)
	v_fma_f32 v61, -v24, v70, v61
	v_mov_b32_e32 v70, 0x10070
	v_fma_f32 v64, -v25, v71, v64
	v_fma_f32 v65, -v26, v72, v65
	v_fma_f32 v74, -v27, v73, v74
	ds_read_b128 v[70:73], v70
	s_waitcnt lgkmcnt(0)
	v_fma_f32 v61, -v28, v70, v61
	v_mov_b32_e32 v70, 0x10080
	v_fma_f32 v64, -v29, v71, v64
	v_fma_f32 v65, -v30, v72, v65
	v_fma_f32 v74, -v31, v73, v74
	ds_read_b128 v[70:73], v70
	s_waitcnt lgkmcnt(0)
	v_fma_f32 v61, -v32, v70, v61
	v_mov_b32_e32 v70, 0x10090
	v_fma_f32 v64, -v33, v71, v64
	v_fma_f32 v65, -v34, v72, v65
	v_fma_f32 v74, -v35, v73, v74
	ds_read_b128 v[70:73], v70
	s_waitcnt lgkmcnt(0)
	v_fma_f32 v61, -v36, v70, v61
	v_mov_b32_e32 v70, 0x100a0
	v_fma_f32 v64, -v37, v71, v64
	v_fma_f32 v65, -v38, v72, v65
	v_fma_f32 v74, -v39, v73, v74
	ds_read_b128 v[70:73], v70
	s_waitcnt lgkmcnt(0)
	v_fma_f32 v61, -v40, v70, v61
	v_mov_b32_e32 v70, 0x100b0
	v_fma_f32 v64, -v41, v71, v64
	v_fma_f32 v65, -v42, v72, v65
	v_fma_f32 v74, -v43, v73, v74
	ds_read_b128 v[70:73], v70
	s_waitcnt lgkmcnt(0)
	v_fma_f32 v61, -v44, v70, v61
	v_mov_b32_e32 v70, 0x100c0
	v_fma_f32 v64, -v45, v71, v64
	v_fma_f32 v65, -v46, v72, v65
	v_fma_f32 v74, -v47, v73, v74
	ds_read_b128 v[70:73], v70
	s_waitcnt lgkmcnt(0)
	v_fma_f32 v61, -v48, v70, v61
	v_mov_b32_e32 v70, 0x100d0
	v_fma_f32 v64, -v49, v71, v64
	v_fma_f32 v65, -v50, v72, v65
	v_fma_f32 v74, -v51, v73, v74
	ds_read_b128 v[70:73], v70
	s_waitcnt lgkmcnt(0)
	v_fma_f32 v61, -v52, v70, v61
	v_mov_b32_e32 v70, 0x100e0
	v_fma_f32 v64, -v53, v71, v64
	v_fma_f32 v65, -v54, v72, v65
	v_fma_f32 v74, -v55, v73, v74
	ds_read_b128 v[70:73], v70
	s_waitcnt lgkmcnt(0)
	v_fma_f32 v64, -v57, v71, v64
	v_mov_b32_e32 v71, 0x100f0
	ds_read_b32 v71, v71
	v_fma_f32 v61, -v56, v70, v61
	v_fma_f32 v65, -v58, v72, v65
	v_fma_f32 v70, -v59, v73, v74
	s_waitcnt lgkmcnt(0)
	v_fma_f32 v61, -v60, v71, v61
	v_add_f32_e32 v61, v64, v61
	v_add_f32_e32 v64, v65, v70
	v_add_f32_e32 v61, v64, v61
	v_mov_b32_e32 v64, 0x10100
	ds_read_b128 v[70:73], v64
	s_waitcnt lgkmcnt(0)
	v_mul_f32_e32 v64, v0, v70
	v_mov_b32_e32 v70, 0x10110
	v_fma_f32 v62, v75, v62, -v64
	v_fma_f32 v64, -v1, v71, 0
	v_fma_f32 v65, -v2, v72, 0
	v_fma_f32 v66, -v3, v73, 0
	ds_read_b128 v[70:73], v70
	s_waitcnt lgkmcnt(0)
	v_fma_f32 v62, -v4, v70, v62
	v_mov_b32_e32 v70, 0x10120
	v_fma_f32 v64, -v5, v71, v64
	v_fma_f32 v65, -v6, v72, v65
	v_fma_f32 v66, -v7, v73, v66
	ds_read_b128 v[70:73], v70
	s_waitcnt lgkmcnt(0)
	v_fma_f32 v62, -v8, v70, v62
	v_mov_b32_e32 v70, 0x10130
	v_fma_f32 v64, -v9, v71, v64
	v_fma_f32 v65, -v10, v72, v65
	v_fma_f32 v66, -v11, v73, v66
	ds_read_b128 v[70:73], v70
	s_waitcnt lgkmcnt(0)
	v_fma_f32 v62, -v12, v70, v62
	v_mov_b32_e32 v70, 0x10140
	v_fma_f32 v64, -v13, v71, v64
	v_fma_f32 v65, -v14, v72, v65
	v_fma_f32 v66, -v15, v73, v66
	ds_read_b128 v[70:73], v70
	s_waitcnt lgkmcnt(0)
	v_fma_f32 v62, -v16, v70, v62
	v_mov_b32_e32 v70, 0x10150
	v_fma_f32 v64, -v17, v71, v64
	v_fma_f32 v65, -v18, v72, v65
	v_fma_f32 v66, -v19, v73, v66
	ds_read_b128 v[70:73], v70
	s_waitcnt lgkmcnt(0)
	v_fma_f32 v62, -v20, v70, v62
	v_mov_b32_e32 v70, 0x10160
	v_fma_f32 v64, -v21, v71, v64
	v_fma_f32 v65, -v22, v72, v65
	v_fma_f32 v66, -v23, v73, v66
	ds_read_b128 v[70:73], v70
	s_waitcnt lgkmcnt(0)
	v_fma_f32 v62, -v24, v70, v62
	v_mov_b32_e32 v70, 0x10170
	v_fma_f32 v64, -v25, v71, v64
	v_fma_f32 v65, -v26, v72, v65
	v_fma_f32 v66, -v27, v73, v66
	ds_read_b128 v[70:73], v70
	s_waitcnt lgkmcnt(0)
	v_fma_f32 v62, -v28, v70, v62
	v_mov_b32_e32 v70, 0x10180
	v_fma_f32 v64, -v29, v71, v64
	v_fma_f32 v65, -v30, v72, v65
	v_fma_f32 v66, -v31, v73, v66
	ds_read_b128 v[70:73], v70
	s_waitcnt lgkmcnt(0)
	v_fma_f32 v62, -v32, v70, v62
	v_mov_b32_e32 v70, 0x10190
	v_fma_f32 v64, -v33, v71, v64
	v_fma_f32 v65, -v34, v72, v65
	v_fma_f32 v66, -v35, v73, v66
	ds_read_b128 v[70:73], v70
	s_waitcnt lgkmcnt(0)
	v_fma_f32 v62, -v36, v70, v62
	v_mov_b32_e32 v70, 0x101a0
	v_fma_f32 v64, -v37, v71, v64
	v_fma_f32 v65, -v38, v72, v65
	v_fma_f32 v66, -v39, v73, v66
	ds_read_b128 v[70:73], v70
	s_waitcnt lgkmcnt(0)
	v_fma_f32 v62, -v40, v70, v62
	v_mov_b32_e32 v70, 0x101b0
	v_fma_f32 v64, -v41, v71, v64
	v_fma_f32 v65, -v42, v72, v65
	v_fma_f32 v66, -v43, v73, v66
	ds_read_b128 v[70:73], v70
	s_waitcnt lgkmcnt(0)
	v_fma_f32 v62, -v44, v70, v62
	v_mov_b32_e32 v70, 0x101c0
	v_fma_f32 v64, -v45, v71, v64
	v_fma_f32 v65, -v46, v72, v65
	v_fma_f32 v66, -v47, v73, v66
	ds_read_b128 v[70:73], v70
	s_waitcnt lgkmcnt(0)
	v_fma_f32 v62, -v48, v70, v62
	v_mov_b32_e32 v70, 0x101d0
	v_fma_f32 v64, -v49, v71, v64
	v_fma_f32 v65, -v50, v72, v65
	v_fma_f32 v66, -v51, v73, v66
	ds_read_b128 v[70:73], v70
	s_waitcnt lgkmcnt(0)
	v_fma_f32 v62, -v52, v70, v62
	v_mov_b32_e32 v70, 0x101e0
	v_fma_f32 v64, -v53, v71, v64
	v_fma_f32 v65, -v54, v72, v65
	v_fma_f32 v66, -v55, v73, v66
	ds_read_b128 v[70:73], v70
	s_waitcnt lgkmcnt(0)
	v_fma_f32 v62, -v56, v70, v62
	v_fma_f32 v70, -v57, v71, v64
	v_mov_b32_e32 v64, 0x101f0
	v_fma_f32 v71, -v58, v72, v65
	ds_read_b64 v[64:65], v64
	v_fma_f32 v66, -v59, v73, v66
	s_waitcnt lgkmcnt(0)
	v_fma_f32 v62, -v60, v64, v62
	v_fma_f32 v64, -v61, v65, v70
	v_add_f32_e32 v62, v62, v64
	v_add_f32_e32 v64, v71, v66
	v_add_f32_e32 v62, v64, v62
	v_mov_b32_e32 v64, 0x10200
	ds_read_b128 v[64:67], v64
	s_waitcnt lgkmcnt(0)
	v_mul_f32_e32 v64, v0, v64
	v_fma_f32 v63, v69, v63, -v64
	v_mov_b32_e32 v64, 0x10210
	v_fma_f32 v69, -v1, v65, 0
	v_fma_f32 v70, -v2, v66, 0
	v_fma_f32 v71, -v3, v67, 0
	ds_read_b128 v[64:67], v64
	s_waitcnt lgkmcnt(0)
	v_fma_f32 v63, -v4, v64, v63
	v_mov_b32_e32 v64, 0x10220
	v_fma_f32 v69, -v5, v65, v69
	v_fma_f32 v70, -v6, v66, v70
	v_fma_f32 v71, -v7, v67, v71
	ds_read_b128 v[64:67], v64
	s_waitcnt lgkmcnt(0)
	v_fma_f32 v63, -v8, v64, v63
	v_mov_b32_e32 v64, 0x10230
	v_fma_f32 v69, -v9, v65, v69
	v_fma_f32 v70, -v10, v66, v70
	v_fma_f32 v71, -v11, v67, v71
	ds_read_b128 v[64:67], v64
	s_waitcnt lgkmcnt(0)
	v_fma_f32 v63, -v12, v64, v63
	v_mov_b32_e32 v64, 0x10240
	v_fma_f32 v69, -v13, v65, v69
	v_fma_f32 v70, -v14, v66, v70
	v_fma_f32 v71, -v15, v67, v71
	ds_read_b128 v[64:67], v64
	s_waitcnt lgkmcnt(0)
	v_fma_f32 v63, -v16, v64, v63
	v_mov_b32_e32 v64, 0x10250
	v_fma_f32 v69, -v17, v65, v69
	v_fma_f32 v70, -v18, v66, v70
	v_fma_f32 v71, -v19, v67, v71
	ds_read_b128 v[64:67], v64
	s_waitcnt lgkmcnt(0)
	v_fma_f32 v63, -v20, v64, v63
	v_mov_b32_e32 v64, 0x10260
	v_fma_f32 v69, -v21, v65, v69
	v_fma_f32 v70, -v22, v66, v70
	v_fma_f32 v71, -v23, v67, v71
	ds_read_b128 v[64:67], v64
	s_waitcnt lgkmcnt(0)
	v_fma_f32 v63, -v24, v64, v63
	v_mov_b32_e32 v64, 0x10270
	v_fma_f32 v69, -v25, v65, v69
	v_fma_f32 v70, -v26, v66, v70
	v_fma_f32 v71, -v27, v67, v71
	ds_read_b128 v[64:67], v64
	s_waitcnt lgkmcnt(0)
	v_fma_f32 v63, -v28, v64, v63
	v_mov_b32_e32 v64, 0x10280
	v_fma_f32 v69, -v29, v65, v69
	v_fma_f32 v70, -v30, v66, v70
	v_fma_f32 v71, -v31, v67, v71
	ds_read_b128 v[64:67], v64
	s_waitcnt lgkmcnt(0)
	v_fma_f32 v63, -v32, v64, v63
	v_mov_b32_e32 v64, 0x10290
	v_fma_f32 v69, -v33, v65, v69
	v_fma_f32 v70, -v34, v66, v70
	v_fma_f32 v71, -v35, v67, v71
	ds_read_b128 v[64:67], v64
	s_waitcnt lgkmcnt(0)
	v_fma_f32 v63, -v36, v64, v63
	v_mov_b32_e32 v64, 0x102a0
	v_fma_f32 v69, -v37, v65, v69
	v_fma_f32 v70, -v38, v66, v70
	v_fma_f32 v71, -v39, v67, v71
	ds_read_b128 v[64:67], v64
	s_waitcnt lgkmcnt(0)
	v_fma_f32 v63, -v40, v64, v63
	v_mov_b32_e32 v64, 0x102b0
	v_fma_f32 v69, -v41, v65, v69
	v_fma_f32 v70, -v42, v66, v70
	v_fma_f32 v71, -v43, v67, v71
	ds_read_b128 v[64:67], v64
	s_waitcnt lgkmcnt(0)
	v_fma_f32 v63, -v44, v64, v63
	v_mov_b32_e32 v64, 0x102c0
	v_fma_f32 v69, -v45, v65, v69
	v_fma_f32 v70, -v46, v66, v70
	v_fma_f32 v71, -v47, v67, v71
	ds_read_b128 v[64:67], v64
	s_waitcnt lgkmcnt(0)
	v_fma_f32 v63, -v48, v64, v63
	v_mov_b32_e32 v64, 0x102d0
	v_fma_f32 v69, -v49, v65, v69
	v_fma_f32 v70, -v50, v66, v70
	v_fma_f32 v71, -v51, v67, v71
	ds_read_b128 v[64:67], v64
	s_waitcnt lgkmcnt(0)
	v_fma_f32 v63, -v52, v64, v63
	v_fma_f32 v64, -v53, v65, v69
	v_fma_f32 v65, -v54, v66, v70
	v_fma_f32 v66, -v55, v67, v71
	v_mov_b32_e32 v67, 0x102e0
	ds_read_b128 v[70:73], v67
	s_waitcnt lgkmcnt(0)
	v_fma_f32 v69, -v57, v71, v64
	v_mov_b32_e32 v64, 0x102f0
	v_fma_f32 v67, -v56, v70, v63
	v_fma_f32 v70, -v58, v72, v65
	v_fma_f32 v63, -v59, v73, v66
	ds_read_b96 v[64:66], v64
	s_waitcnt lgkmcnt(0)
	v_fma_f32 v64, -v60, v64, v67
	v_fma_f32 v65, -v61, v65, v69
	v_fma_f32 v66, -v62, v66, v70
	v_add_f32_e32 v64, v64, v65
	v_add_f32_e32 v63, v63, v66
	v_add_f32_e32 v63, v64, v63
	s_and_saveexec_b64 s[2:3], s[42:43]
	s_xor_b64 s[40:41], exec, s[2:3]
	s_cbranch_execz .LBB0_419
	v_mov_b32_e32 v69, v129
	v_lshl_add_u64 v[64:65], v[68:69], 1, s[56:57]
	v_cvt_pk_bf16_f32 v0, -v0, s0
	v_lshl_add_u64 v[66:67], v[64:65], 0, s[0:1]
	global_store_short v[66:67], v0, off offset:-128
	v_add_co_u32_e32 v0, vcc, 0x4000, v64
	v_cvt_pk_bf16_f32 v68, -v1, s0
	s_nop 0
	v_addc_co_u32_e32 v1, vcc, 0, v65, vcc
	global_store_short v[0:1], v68, off
	v_cvt_pk_bf16_f32 v0, -v2, s0
	global_store_short v[66:67], v0, off offset:128
	v_cvt_pk_bf16_f32 v0, -v3, s0
	global_store_short v[66:67], v0, off offset:256
	v_cvt_pk_bf16_f32 v0, -v4, s0
	global_store_short v[66:67], v0, off offset:384
	v_cvt_pk_bf16_f32 v0, -v5, s0
	global_store_short v[66:67], v0, off offset:512
	v_cvt_pk_bf16_f32 v0, -v6, s0
	global_store_short v[66:67], v0, off offset:640
	v_cvt_pk_bf16_f32 v0, -v7, s0
	global_store_short v[66:67], v0, off offset:768
	v_cvt_pk_bf16_f32 v0, -v8, s0
	global_store_short v[66:67], v0, off offset:896
	v_cvt_pk_bf16_f32 v0, -v9, s0
	global_store_short v[66:67], v0, off offset:1024
	v_cvt_pk_bf16_f32 v0, -v10, s0
	global_store_short v[66:67], v0, off offset:1152
	v_cvt_pk_bf16_f32 v0, -v11, s0
	global_store_short v[66:67], v0, off offset:1280
	v_cvt_pk_bf16_f32 v0, -v12, s0
	global_store_short v[66:67], v0, off offset:1408
	v_cvt_pk_bf16_f32 v0, -v13, s0
	global_store_short v[66:67], v0, off offset:1536
	v_cvt_pk_bf16_f32 v0, -v14, s0
	global_store_short v[66:67], v0, off offset:1664
	v_cvt_pk_bf16_f32 v0, -v15, s0
	global_store_short v[66:67], v0, off offset:1792
	v_cvt_pk_bf16_f32 v0, -v16, s0
	global_store_short v[66:67], v0, off offset:1920
	v_cvt_pk_bf16_f32 v0, -v17, s0
	global_store_short v[66:67], v0, off offset:2048
	v_cvt_pk_bf16_f32 v0, -v18, s0
	global_store_short v[66:67], v0, off offset:2176
	v_cvt_pk_bf16_f32 v0, -v19, s0
	global_store_short v[66:67], v0, off offset:2304
	v_cvt_pk_bf16_f32 v0, -v20, s0
	global_store_short v[66:67], v0, off offset:2432
	v_cvt_pk_bf16_f32 v0, -v21, s0
	global_store_short v[66:67], v0, off offset:2560
	v_cvt_pk_bf16_f32 v0, -v22, s0
	global_store_short v[66:67], v0, off offset:2688
	v_cvt_pk_bf16_f32 v0, -v23, s0
	global_store_short v[66:67], v0, off offset:2816
	v_cvt_pk_bf16_f32 v0, -v24, s0
	global_store_short v[66:67], v0, off offset:2944
	v_cvt_pk_bf16_f32 v0, -v25, s0
	global_store_short v[66:67], v0, off offset:3072
	v_cvt_pk_bf16_f32 v0, -v26, s0
	global_store_short v[66:67], v0, off offset:3200
	v_cvt_pk_bf16_f32 v0, -v27, s0
	global_store_short v[66:67], v0, off offset:3328
	v_cvt_pk_bf16_f32 v0, -v28, s0
	global_store_short v[66:67], v0, off offset:3456
	v_cvt_pk_bf16_f32 v0, -v29, s0
	global_store_short v[66:67], v0, off offset:3584
	v_cvt_pk_bf16_f32 v0, -v30, s0
	global_store_short v[66:67], v0, off offset:3712
	v_cvt_pk_bf16_f32 v0, -v31, s0
	global_store_short v[66:67], v0, off offset:3840
	v_cvt_pk_bf16_f32 v0, -v32, s0
	s_movk_i32 s2, 0x5000
	global_store_short v[66:67], v0, off offset:3968
	v_add_co_u32_e32 v0, vcc, s2, v64
	v_cvt_pk_bf16_f32 v2, -v33, s0
	s_nop 0
	v_addc_co_u32_e32 v1, vcc, 0, v65, vcc
	global_store_short v[0:1], v2, off
	v_cvt_pk_bf16_f32 v2, -v34, s0
	global_store_short v[0:1], v2, off offset:128
	v_cvt_pk_bf16_f32 v2, -v35, s0
	global_store_short v[0:1], v2, off offset:256
	v_cvt_pk_bf16_f32 v2, -v36, s0
	global_store_short v[0:1], v2, off offset:384
	v_cvt_pk_bf16_f32 v2, -v37, s0
	global_store_short v[0:1], v2, off offset:512
	v_cvt_pk_bf16_f32 v2, -v38, s0
	global_store_short v[0:1], v2, off offset:640
	v_cvt_pk_bf16_f32 v2, -v39, s0
	global_store_short v[0:1], v2, off offset:768
	v_cvt_pk_bf16_f32 v2, -v40, s0
	global_store_short v[0:1], v2, off offset:896
	v_cvt_pk_bf16_f32 v2, -v41, s0
	global_store_short v[0:1], v2, off offset:1024
	v_cvt_pk_bf16_f32 v2, -v42, s0
	global_store_short v[0:1], v2, off offset:1152
	v_cvt_pk_bf16_f32 v2, -v43, s0
	global_store_short v[0:1], v2, off offset:1280
	v_cvt_pk_bf16_f32 v2, -v44, s0
	global_store_short v[0:1], v2, off offset:1408
	v_cvt_pk_bf16_f32 v2, -v45, s0
	global_store_short v[0:1], v2, off offset:1536
	v_cvt_pk_bf16_f32 v2, -v46, s0
	global_store_short v[0:1], v2, off offset:1664
	v_cvt_pk_bf16_f32 v2, -v47, s0
	global_store_short v[0:1], v2, off offset:1792
	v_cvt_pk_bf16_f32 v2, -v48, s0
	global_store_short v[0:1], v2, off offset:1920
	v_cvt_pk_bf16_f32 v2, -v49, s0
	global_store_short v[0:1], v2, off offset:2048
	v_cvt_pk_bf16_f32 v2, -v50, s0
	global_store_short v[0:1], v2, off offset:2176
	v_cvt_pk_bf16_f32 v2, -v51, s0
	global_store_short v[0:1], v2, off offset:2304
	v_cvt_pk_bf16_f32 v2, -v52, s0
	global_store_short v[0:1], v2, off offset:2432
	v_cvt_pk_bf16_f32 v2, -v53, s0
	global_store_short v[0:1], v2, off offset:2560
	v_cvt_pk_bf16_f32 v2, -v54, s0
	global_store_short v[0:1], v2, off offset:2688
	v_cvt_pk_bf16_f32 v2, -v55, s0
	global_store_short v[0:1], v2, off offset:2816
	v_cvt_pk_bf16_f32 v2, -v56, s0
	global_store_short v[0:1], v2, off offset:2944
	v_cvt_pk_bf16_f32 v2, -v57, s0
	global_store_short v[0:1], v2, off offset:3072
	v_cvt_pk_bf16_f32 v2, -v58, s0
	global_store_short v[0:1], v2, off offset:3200
	v_cvt_pk_bf16_f32 v2, -v59, s0
	global_store_short v[0:1], v2, off offset:3328
	v_cvt_pk_bf16_f32 v2, -v60, s0
	global_store_short v[0:1], v2, off offset:3456
	v_cvt_pk_bf16_f32 v2, -v61, s0
	global_store_short v[0:1], v2, off offset:3584
	v_cvt_pk_bf16_f32 v2, -v62, s0
	global_store_short v[0:1], v2, off offset:3712
	v_cvt_pk_bf16_f32 v2, -v63, s0
	global_store_short v[0:1], v2, off offset:3840
